# v35: v34 (P6 early prefetch, head SALU sink, attention back-edge edit) + mid-segment s_setprio flip pair -> s_nop in all six GEMM loops
# speedup vs baseline: 1.0062x; 1.0006x over previous
; #define PG8_STAGE(bufoff, gbase, voff) do { _Pragma("unroll") for (int _i = 0; _i < 2; ++_i) \
;         __builtin_amdgcn_global_load_lds((const unsigned*)((const char*)(gbase) + (voff)[_i]), (LAS unsigned*)(lds + (bufoff) + ldsw + _i * 8192), 16, 0, 0); } while (0)
; #define PG8_LDA(dst, b, h) do { _Pragma("unroll") for (int m = 0; m < 4; ++m) _Pragma("unroll") for (int k = 0; k < 2; ++k) dst[m][k] = *(const LAS bf16x8*)(lds + PG8_SA(b, h) + aoff + m * 2048 + k * 1024); } while (0)
; #define PG8_LDB(dst, b, h) do { _Pragma("unroll") for (int n = 0; n < 2; ++n) _Pragma("unroll") for (int k = 0; k < 2; ++k) dst[n][k] = *(const LAS bf16x8*)(lds + PG8_SB(b, h) + boff + n * 2048 + k * 1024); } while (0)
; #define PG8_MMA(ai, bj, At, Bt) do { __builtin_amdgcn_s_setprio(1); _Pragma("unroll") for (int m = 0; m < 4; ++m) _Pragma("unroll") for (int n = 0; n < 2; ++n) _Pragma("unroll") for (int k = 0; k < 2; ++k) \
;         acc[ai][bj][m][n] = __builtin_amdgcn_mfma_f32_16x16x32_bf16(Bt[n][k], At[m][k], acc[ai][bj][m][n], 0, 0, 0); __builtin_amdgcn_s_setprio(0); } while (0)
; #define PG8_WAIT_V(n) asm volatile("s_waitcnt vmcnt(" #n ")" ::: "memory")
; #define PG8_WAIT_L(n) asm volatile("s_waitcnt lgkmcnt(" #n ")" ::: "memory")
; #define PG8_BAR __builtin_amdgcn_s_barrier()
; template <class Epi, class Sched, bool ALIGN_EPI, bool SP2>
; __device__ __forceinline__ void gemm_phase(LAS unsigned char* lds, const Gemm g, const Sched& S, const Epi& E) {
;     ...
;         for (int t = 0; t < nt; t += 2) {
;             const bool last = (t == nt - 2);
;             const char* a1 = cA + (size_t)(t + 1) * kstep;
;             const char* a2 = last ? nA : cA + (size_t)(t + 2) * kstep; const char* b2 = last ? nB : cB + (size_t)(t + 2) * kstep;
;             const char* a3 = a2 + kstep; const char* b3 = b2 + kstep;
;             if constexpr (SP2) {
;             PG8_LDB(B0, 0, 0); PG8_LDB(B1, 0, 1); PG8_SCHED; PG8_LDA(At, 0, 0); PG8_STAGE(PG8_SA(1, 1), a1 + hstep, voffA);
;             PG8_WAIT_V(8); PG8_WAIT_L(0); PG8_BAR; PG8_MMA(0, 0, At, B0); PG8_MMA(0, 1, At, B1); PG8_BAR; PG8_SCHED;
;             PG8_LDA(At, 0, 1); PG8_STAGE(PG8_SB(0, 0), b2, voffB); PG8_STAGE(PG8_SB(0, 1), b2 + hstep, voffB); PG8_STAGE(PG8_SA(0, 0), a2, voffA);
;             PG8_WAIT_V(8); PG8_WAIT_L(0); PG8_BAR; PG8_MMA(1, 0, At, B0); PG8_MMA(1, 1, At, B1); PG8_BAR; PG8_SCHED;
.LBB0_216:
	s_add_i32 m0, s71, 0xc000
	s_nop 0
	global_load_lds_dwordx4 v160, s[6:7]
	s_add_i32 m0, s71, 0xe000
	s_nop 0
	global_load_lds_dwordx4 v162, s[6:7]
	ds_read_b128 v[128:131], v177
	ds_read_b128 v[132:135], v177 offset:1024
	ds_read_b128 v[136:139], v177 offset:2048
	ds_read_b128 v[140:143], v177 offset:3072
	ds_read_b128 v[168:171], v178
	ds_read_b128 v[184:187], v178 offset:1024
	ds_read_b128 v[188:191], v178 offset:2048
	ds_read_b128 v[192:195], v178 offset:3072
	ds_read_b128 v[196:199], v179
	ds_read_b128 v[200:203], v179 offset:1024
	ds_read_b128 v[204:207], v179 offset:2048
	ds_read_b128 v[208:211], v179 offset:3072
	ds_read_b128 v[212:215], v179 offset:4096
	ds_read_b128 v[216:219], v179 offset:5120
	ds_read_b128 v[220:223], v179 offset:6144
	ds_read_b128 v[224:227], v179 offset:7168
	s_add_u32 s8, s6, 0xfffc0080
	s_addc_u32 s9, s7, -1
	s_cmp_eq_u32 s43, 12
	s_cselect_b32 s11, s2, s9
	s_cselect_b32 s10, s3, s8
	s_cselect_b32 s9, s5, s42
	s_cselect_b32 s8, s12, s13
	s_waitcnt vmcnt(8)
	s_waitcnt lgkmcnt(0)
	s_barrier
	s_setprio 1
	s_waitcnt lgkmcnt(0)
	v_mfma_f32_16x16x32_bf16 v[124:127], v[128:131], v[196:199], v[124:127]
	v_mfma_f32_16x16x32_bf16 v[120:123], v[136:139], v[196:199], v[120:123]
	v_mfma_f32_16x16x32_bf16 v[116:119], v[128:131], v[204:207], v[116:119]
	v_mfma_f32_16x16x32_bf16 v[112:115], v[136:139], v[204:207], v[112:115]
	v_mfma_f32_16x16x32_bf16 v[108:111], v[128:131], v[212:215], v[108:111]
	v_mfma_f32_16x16x32_bf16 v[104:107], v[136:139], v[212:215], v[104:107]
	v_mfma_f32_16x16x32_bf16 v[100:103], v[128:131], v[220:223], v[100:103]
	v_mfma_f32_16x16x32_bf16 v[96:99], v[136:139], v[220:223], v[96:99]
	v_mfma_f32_16x16x32_bf16 v[124:127], v[132:135], v[200:203], v[124:127]
	v_mfma_f32_16x16x32_bf16 v[120:123], v[140:143], v[200:203], v[120:123]
	v_mfma_f32_16x16x32_bf16 v[116:119], v[132:135], v[208:211], v[116:119]
	v_mfma_f32_16x16x32_bf16 v[112:115], v[140:143], v[208:211], v[112:115]
	v_mfma_f32_16x16x32_bf16 v[108:111], v[132:135], v[216:219], v[108:111]
	v_mfma_f32_16x16x32_bf16 v[104:107], v[140:143], v[216:219], v[104:107]
	v_mfma_f32_16x16x32_bf16 v[100:103], v[132:135], v[224:227], v[100:103]
	v_mfma_f32_16x16x32_bf16 v[96:99], v[140:143], v[224:227], v[96:99]
	s_nop 0
	s_nop 0
	v_mfma_f32_16x16x32_bf16 v[60:63], v[168:171], v[196:199], v[60:63]
	v_mfma_f32_16x16x32_bf16 v[56:59], v[188:191], v[196:199], v[56:59]
	v_mfma_f32_16x16x32_bf16 v[52:55], v[168:171], v[204:207], v[52:55]
	v_mfma_f32_16x16x32_bf16 v[48:51], v[188:191], v[204:207], v[48:51]
	v_mfma_f32_16x16x32_bf16 v[44:47], v[168:171], v[212:215], v[44:47]
	v_mfma_f32_16x16x32_bf16 v[40:43], v[188:191], v[212:215], v[40:43]
	v_mfma_f32_16x16x32_bf16 v[36:39], v[168:171], v[220:223], v[36:39]
	v_mfma_f32_16x16x32_bf16 v[32:35], v[188:191], v[220:223], v[32:35]
	v_mfma_f32_16x16x32_bf16 v[60:63], v[184:187], v[200:203], v[60:63]
	v_mfma_f32_16x16x32_bf16 v[56:59], v[192:195], v[200:203], v[56:59]
	v_mfma_f32_16x16x32_bf16 v[52:55], v[184:187], v[208:211], v[52:55]
	v_mfma_f32_16x16x32_bf16 v[48:51], v[192:195], v[208:211], v[48:51]
	v_mfma_f32_16x16x32_bf16 v[44:47], v[184:187], v[216:219], v[44:47]
	v_mfma_f32_16x16x32_bf16 v[40:43], v[192:195], v[216:219], v[40:43]
	v_mfma_f32_16x16x32_bf16 v[36:39], v[184:187], v[224:227], v[36:39]
	v_mfma_f32_16x16x32_bf16 v[32:35], v[192:195], v[224:227], v[32:35]
	s_setprio 0
	s_barrier
	s_add_i32 s44, s74, s70
	s_mov_b32 m0, s44
	s_nop 0
	global_load_lds_dwordx4 v146, s[8:9]
	s_add_i32 m0, s44, 0x2000
	s_add_u32 s44, s8, 0x40000
	s_addc_u32 s45, s9, 0
	s_add_i32 s50, s75, s70
	global_load_lds_dwordx4 v150, s[8:9]
	s_mov_b32 m0, s50
	s_nop 0
	global_load_lds_dwordx4 v146, s[44:45]
	s_add_i32 m0, s50, 0x2000
	s_nop 0
	global_load_lds_dwordx4 v150, s[44:45]
	s_mov_b32 m0, s71
	s_nop 0
	global_load_lds_dwordx4 v144, s[10:11]
	s_mov_b32 m0, s72
	s_nop 0
	global_load_lds_dwordx4 v148, s[10:11]
	ds_read_b128 v[196:199], v179 offset:16384
	ds_read_b128 v[200:203], v179 offset:17408
	ds_read_b128 v[204:207], v179 offset:18432
	ds_read_b128 v[208:211], v179 offset:19456
	ds_read_b128 v[212:215], v179 offset:20480
	ds_read_b128 v[216:219], v179 offset:21504
	ds_read_b128 v[220:223], v179 offset:22528
	ds_read_b128 v[224:227], v179 offset:23552
	s_waitcnt vmcnt(8)
	s_waitcnt lgkmcnt(0)
	s_barrier
	s_setprio 1
	s_waitcnt lgkmcnt(0)
	v_mfma_f32_16x16x32_bf16 v[92:95], v[128:131], v[196:199], v[92:95]
	v_mfma_f32_16x16x32_bf16 v[88:91], v[136:139], v[196:199], v[88:91]
	v_mfma_f32_16x16x32_bf16 v[84:87], v[128:131], v[204:207], v[84:87]
	v_mfma_f32_16x16x32_bf16 v[80:83], v[136:139], v[204:207], v[80:83]
	v_mfma_f32_16x16x32_bf16 v[76:79], v[128:131], v[212:215], v[76:79]
	v_mfma_f32_16x16x32_bf16 v[72:75], v[136:139], v[212:215], v[72:75]
	v_mfma_f32_16x16x32_bf16 v[68:71], v[128:131], v[220:223], v[68:71]
	v_mfma_f32_16x16x32_bf16 v[64:67], v[136:139], v[220:223], v[64:67]
	v_mfma_f32_16x16x32_bf16 v[92:95], v[132:135], v[200:203], v[92:95]
	v_mfma_f32_16x16x32_bf16 v[88:91], v[140:143], v[200:203], v[88:91]
	v_mfma_f32_16x16x32_bf16 v[84:87], v[132:135], v[208:211], v[84:87]
	v_mfma_f32_16x16x32_bf16 v[80:83], v[140:143], v[208:211], v[80:83]
	v_mfma_f32_16x16x32_bf16 v[76:79], v[132:135], v[216:219], v[76:79]
	v_mfma_f32_16x16x32_bf16 v[72:75], v[140:143], v[216:219], v[72:75]
	v_mfma_f32_16x16x32_bf16 v[68:71], v[132:135], v[224:227], v[68:71]
	v_mfma_f32_16x16x32_bf16 v[64:67], v[140:143], v[224:227], v[64:67]
	s_nop 0
	s_nop 0
	v_mfma_f32_16x16x32_bf16 v[28:31], v[168:171], v[196:199], v[28:31]
	v_mfma_f32_16x16x32_bf16 v[24:27], v[188:191], v[196:199], v[24:27]
	v_mfma_f32_16x16x32_bf16 v[20:23], v[168:171], v[204:207], v[20:23]
	v_mfma_f32_16x16x32_bf16 v[16:19], v[188:191], v[204:207], v[16:19]
	v_mfma_f32_16x16x32_bf16 v[12:15], v[168:171], v[212:215], v[12:15]
	v_mfma_f32_16x16x32_bf16 v[8:11], v[188:191], v[212:215], v[8:11]
	v_mfma_f32_16x16x32_bf16 v[4:7], v[168:171], v[220:223], v[4:7]
	v_mfma_f32_16x16x32_bf16 v[0:3], v[188:191], v[220:223], v[0:3]
	v_mfma_f32_16x16x32_bf16 v[28:31], v[184:187], v[200:203], v[28:31]
	v_mfma_f32_16x16x32_bf16 v[24:27], v[192:195], v[200:203], v[24:27]
	v_mfma_f32_16x16x32_bf16 v[20:23], v[184:187], v[208:211], v[20:23]
	v_mfma_f32_16x16x32_bf16 v[16:19], v[192:195], v[208:211], v[16:19]
	v_mfma_f32_16x16x32_bf16 v[12:15], v[184:187], v[216:219], v[12:15]
	v_mfma_f32_16x16x32_bf16 v[8:11], v[192:195], v[216:219], v[8:11]
	v_mfma_f32_16x16x32_bf16 v[4:7], v[184:187], v[224:227], v[4:7]
	v_mfma_f32_16x16x32_bf16 v[0:3], v[192:195], v[224:227], v[0:3]
	s_setprio 0
	s_barrier
; #define PG8_STAGE(bufoff, gbase, voff) do { _Pragma("unroll") for (int _i = 0; _i < 2; ++_i) \
;         __builtin_amdgcn_global_load_lds((const unsigned*)((const char*)(gbase) + (voff)[_i]), (LAS unsigned*)(lds + (bufoff) + ldsw + _i * 8192), 16, 0, 0); } while (0)
; #define PG8_LDA(dst, b, h) do { _Pragma("unroll") for (int m = 0; m < 4; ++m) _Pragma("unroll") for (int k = 0; k < 2; ++k) dst[m][k] = *(const LAS bf16x8*)(lds + PG8_SA(b, h) + aoff + m * 2048 + k * 1024); } while (0)
; #define PG8_LDB(dst, b, h) do { _Pragma("unroll") for (int n = 0; n < 2; ++n) _Pragma("unroll") for (int k = 0; k < 2; ++k) dst[n][k] = *(const LAS bf16x8*)(lds + PG8_SB(b, h) + boff + n * 2048 + k * 1024); } while (0)
; #define PG8_MMA(ai, bj, At, Bt) do { __builtin_amdgcn_s_setprio(1); _Pragma("unroll") for (int m = 0; m < 4; ++m) _Pragma("unroll") for (int n = 0; n < 2; ++n) _Pragma("unroll") for (int k = 0; k < 2; ++k) \
;         acc[ai][bj][m][n] = __builtin_amdgcn_mfma_f32_16x16x32_bf16(Bt[n][k], At[m][k], acc[ai][bj][m][n], 0, 0, 0); __builtin_amdgcn_s_setprio(0); } while (0)
; #define PG8_WAIT_V(n) asm volatile("s_waitcnt vmcnt(" #n ")" ::: "memory")
; #define PG8_WAIT_L(n) asm volatile("s_waitcnt lgkmcnt(" #n ")" ::: "memory")
; #define PG8_BAR __builtin_amdgcn_s_barrier()
; #define PG8_SCHED __builtin_amdgcn_sched_barrier(0)
; template <class Epi, class Sched, bool ALIGN_EPI, bool SP2>
; __device__ __forceinline__ void gemm_phase(LAS unsigned char* lds, const Gemm g, const Sched& S, const Epi& E) {
;     ...
;             PG8_LDB(B0, 1, 0); PG8_LDB(B1, 1, 1); PG8_SCHED; PG8_LDA(At, 1, 0); PG8_STAGE(PG8_SA(0, 1), a2 + hstep, voffA);
;             PG8_WAIT_V(8); PG8_WAIT_L(0); PG8_BAR; PG8_MMA(0, 0, At, B0); PG8_MMA(0, 1, At, B1); PG8_BAR; PG8_SCHED;
;             PG8_LDA(At, 1, 1); PG8_STAGE(PG8_SB(1, 0), b3, voffB); PG8_STAGE(PG8_SB(1, 1), b3 + hstep, voffB); PG8_STAGE(PG8_SA(1, 0), a3, voffA);
;             PG8_WAIT_V(8); PG8_WAIT_L(0); PG8_BAR; PG8_MMA(1, 0, At, B0); PG8_MMA(1, 1, At, B1); PG8_BAR; PG8_SCHED;
	s_add_i32 s44, 0, 0x18000
	s_add_i32 s45, 0, 0x1c000
	v_add_u32_e32 v140, s44, v174
	v_add_u32_e32 v152, s45, v174
	s_add_u32 s10, s10, 0x40000
	s_addc_u32 s11, s11, 0
	s_mov_b32 m0, s73
	s_nop 0
	global_load_lds_dwordx4 v144, s[10:11]
	s_mov_b32 m0, s82
	s_nop 0
	global_load_lds_dwordx4 v148, s[10:11]
	ds_read_b128 v[128:131], v140
	ds_read_b128 v[132:135], v140 offset:1024
	ds_read_b128 v[136:139], v140 offset:2048
	ds_read_b128 v[140:143], v140 offset:3072
	ds_read_b128 v[168:171], v152
	ds_read_b128 v[184:187], v152 offset:1024
	ds_read_b128 v[188:191], v152 offset:2048
	ds_read_b128 v[192:195], v152 offset:3072
	ds_read_b128 v[196:199], v179 offset:32768
	ds_read_b128 v[200:203], v179 offset:33792
	ds_read_b128 v[204:207], v179 offset:34816
	ds_read_b128 v[208:211], v179 offset:35840
	ds_read_b128 v[212:215], v179 offset:36864
	ds_read_b128 v[216:219], v179 offset:37888
	ds_read_b128 v[220:223], v179 offset:38912
	ds_read_b128 v[224:227], v179 offset:39936
	s_waitcnt vmcnt(8)
	s_waitcnt lgkmcnt(0)
	s_barrier
	s_setprio 1
	s_waitcnt lgkmcnt(0)
	v_mfma_f32_16x16x32_bf16 v[124:127], v[128:131], v[196:199], v[124:127]
	v_mfma_f32_16x16x32_bf16 v[120:123], v[136:139], v[196:199], v[120:123]
	v_mfma_f32_16x16x32_bf16 v[116:119], v[128:131], v[204:207], v[116:119]
	v_mfma_f32_16x16x32_bf16 v[112:115], v[136:139], v[204:207], v[112:115]
	v_mfma_f32_16x16x32_bf16 v[108:111], v[128:131], v[212:215], v[108:111]
	v_mfma_f32_16x16x32_bf16 v[104:107], v[136:139], v[212:215], v[104:107]
	v_mfma_f32_16x16x32_bf16 v[100:103], v[128:131], v[220:223], v[100:103]
	v_mfma_f32_16x16x32_bf16 v[96:99], v[136:139], v[220:223], v[96:99]
	v_mfma_f32_16x16x32_bf16 v[124:127], v[132:135], v[200:203], v[124:127]
	v_mfma_f32_16x16x32_bf16 v[120:123], v[140:143], v[200:203], v[120:123]
	v_mfma_f32_16x16x32_bf16 v[116:119], v[132:135], v[208:211], v[116:119]
	v_mfma_f32_16x16x32_bf16 v[112:115], v[140:143], v[208:211], v[112:115]
	v_mfma_f32_16x16x32_bf16 v[108:111], v[132:135], v[216:219], v[108:111]
	v_mfma_f32_16x16x32_bf16 v[104:107], v[140:143], v[216:219], v[104:107]
	v_mfma_f32_16x16x32_bf16 v[100:103], v[132:135], v[224:227], v[100:103]
	v_mfma_f32_16x16x32_bf16 v[96:99], v[140:143], v[224:227], v[96:99]
	s_nop 0
	s_nop 0
	v_mfma_f32_16x16x32_bf16 v[60:63], v[168:171], v[196:199], v[60:63]
	v_mfma_f32_16x16x32_bf16 v[56:59], v[188:191], v[196:199], v[56:59]
	v_mfma_f32_16x16x32_bf16 v[52:55], v[168:171], v[204:207], v[52:55]
	v_mfma_f32_16x16x32_bf16 v[48:51], v[188:191], v[204:207], v[48:51]
	v_mfma_f32_16x16x32_bf16 v[44:47], v[168:171], v[212:215], v[44:47]
	v_mfma_f32_16x16x32_bf16 v[40:43], v[188:191], v[212:215], v[40:43]
	v_mfma_f32_16x16x32_bf16 v[36:39], v[168:171], v[220:223], v[36:39]
	v_mfma_f32_16x16x32_bf16 v[32:35], v[188:191], v[220:223], v[32:35]
	v_mfma_f32_16x16x32_bf16 v[60:63], v[184:187], v[200:203], v[60:63]
	v_mfma_f32_16x16x32_bf16 v[56:59], v[192:195], v[200:203], v[56:59]
	v_mfma_f32_16x16x32_bf16 v[52:55], v[184:187], v[208:211], v[52:55]
	v_mfma_f32_16x16x32_bf16 v[48:51], v[192:195], v[208:211], v[48:51]
	v_mfma_f32_16x16x32_bf16 v[44:47], v[184:187], v[216:219], v[44:47]
	v_mfma_f32_16x16x32_bf16 v[40:43], v[192:195], v[216:219], v[40:43]
	v_mfma_f32_16x16x32_bf16 v[36:39], v[184:187], v[224:227], v[36:39]
	v_mfma_f32_16x16x32_bf16 v[32:35], v[192:195], v[224:227], v[32:35]
	s_setprio 0
	s_barrier
	s_add_u32 s100, s10, 0xfffc0080
	s_addc_u32 s101, s11, -1
	s_add_u32 s98, s8, 0x80
	s_addc_u32 s99, s9, 0
	s_add_i32 s10, s44, s70
	s_mov_b32 m0, s10
	s_nop 0
	global_load_lds_dwordx4 v146, s[98:99]
	s_add_i32 m0, s10, 0x2000
	s_add_u32 s8, s8, 0x40080
	s_addc_u32 s9, s9, 0
	s_add_i32 s10, s45, s70
	global_load_lds_dwordx4 v150, s[98:99]
	s_mov_b32 m0, s10
	s_nop 0
	global_load_lds_dwordx4 v146, s[8:9]
	s_add_i32 m0, s10, 0x2000
	s_nop 0
	global_load_lds_dwordx4 v150, s[8:9]
	s_mov_b32 m0, s83
	s_nop 0
	global_load_lds_dwordx4 v144, s[100:101]
	s_mov_b32 m0, s84
	s_nop 0
	global_load_lds_dwordx4 v148, s[100:101]
	ds_read_b128 v[196:199], v179 offset:49152
	ds_read_b128 v[200:203], v179 offset:50176
	ds_read_b128 v[204:207], v179 offset:51200
	ds_read_b128 v[208:211], v179 offset:52224
	ds_read_b128 v[212:215], v179 offset:53248
	ds_read_b128 v[216:219], v179 offset:54272
	ds_read_b128 v[220:223], v179 offset:55296
	ds_read_b128 v[224:227], v179 offset:56320
	s_waitcnt vmcnt(8)
	s_waitcnt lgkmcnt(0)
	s_barrier
	s_setprio 1
	s_waitcnt lgkmcnt(0)
	v_mfma_f32_16x16x32_bf16 v[92:95], v[128:131], v[196:199], v[92:95]
	v_mfma_f32_16x16x32_bf16 v[88:91], v[136:139], v[196:199], v[88:91]
	v_mfma_f32_16x16x32_bf16 v[84:87], v[128:131], v[204:207], v[84:87]
	v_mfma_f32_16x16x32_bf16 v[80:83], v[136:139], v[204:207], v[80:83]
	v_mfma_f32_16x16x32_bf16 v[76:79], v[128:131], v[212:215], v[76:79]
	v_mfma_f32_16x16x32_bf16 v[72:75], v[136:139], v[212:215], v[72:75]
	v_mfma_f32_16x16x32_bf16 v[68:71], v[128:131], v[220:223], v[68:71]
	v_mfma_f32_16x16x32_bf16 v[64:67], v[136:139], v[220:223], v[64:67]
	v_mfma_f32_16x16x32_bf16 v[92:95], v[132:135], v[200:203], v[92:95]
	v_mfma_f32_16x16x32_bf16 v[88:91], v[140:143], v[200:203], v[88:91]
	v_mfma_f32_16x16x32_bf16 v[84:87], v[132:135], v[208:211], v[84:87]
	v_mfma_f32_16x16x32_bf16 v[80:83], v[140:143], v[208:211], v[80:83]
	v_mfma_f32_16x16x32_bf16 v[76:79], v[132:135], v[216:219], v[76:79]
	v_mfma_f32_16x16x32_bf16 v[72:75], v[140:143], v[216:219], v[72:75]
	v_mfma_f32_16x16x32_bf16 v[68:71], v[132:135], v[224:227], v[68:71]
	v_mfma_f32_16x16x32_bf16 v[64:67], v[140:143], v[224:227], v[64:67]
	s_nop 0
	s_nop 0
	v_mfma_f32_16x16x32_bf16 v[28:31], v[168:171], v[196:199], v[28:31]
	v_mfma_f32_16x16x32_bf16 v[24:27], v[188:191], v[196:199], v[24:27]
	v_mfma_f32_16x16x32_bf16 v[20:23], v[168:171], v[204:207], v[20:23]
	v_mfma_f32_16x16x32_bf16 v[16:19], v[188:191], v[204:207], v[16:19]
	v_mfma_f32_16x16x32_bf16 v[12:15], v[168:171], v[212:215], v[12:15]
	v_mfma_f32_16x16x32_bf16 v[8:11], v[188:191], v[212:215], v[8:11]
	v_mfma_f32_16x16x32_bf16 v[4:7], v[168:171], v[220:223], v[4:7]
	v_mfma_f32_16x16x32_bf16 v[0:3], v[188:191], v[220:223], v[0:3]
	v_mfma_f32_16x16x32_bf16 v[28:31], v[184:187], v[200:203], v[28:31]
	v_mfma_f32_16x16x32_bf16 v[24:27], v[192:195], v[200:203], v[24:27]
	v_mfma_f32_16x16x32_bf16 v[20:23], v[184:187], v[208:211], v[20:23]
	v_mfma_f32_16x16x32_bf16 v[16:19], v[192:195], v[208:211], v[16:19]
	v_mfma_f32_16x16x32_bf16 v[12:15], v[184:187], v[216:219], v[12:15]
	v_mfma_f32_16x16x32_bf16 v[8:11], v[192:195], v[216:219], v[8:11]
	v_mfma_f32_16x16x32_bf16 v[4:7], v[184:187], v[224:227], v[4:7]
	v_mfma_f32_16x16x32_bf16 v[0:3], v[192:195], v[224:227], v[0:3]
	s_setprio 0
	s_barrier
	s_add_i32 s43, s43, 2
	s_add_u32 s6, s6, 0x100
	s_addc_u32 s7, s7, 0
	s_add_u32 s13, s13, 0x100
	s_addc_u32 s42, s42, 0
	s_cmp_gt_u32 s43, 13
	s_cbranch_scc0 .LBB0_216
	s_and_b64 vcc, exec, s[34:35]
	s_cbranch_vccnz .LBB0_221
	v_lshl_add_u32 v168, s4, 8, v155
	s_cmp_lg_u32 s16, 2
	s_mov_b64 s[4:5], -1
	s_cbranch_scc1 .LBB0_222

; #define PG8_STAGE(bufoff, gbase, voff) do { _Pragma("unroll") for (int _i = 0; _i < 2; ++_i) \
;         __builtin_amdgcn_global_load_lds((const unsigned*)((const char*)(gbase) + (voff)[_i]), (LAS unsigned*)(lds + (bufoff) + ldsw + _i * 8192), 16, 0, 0); } while (0)
; #define PG8_LDA(dst, b, h) do { _Pragma("unroll") for (int m = 0; m < 4; ++m) _Pragma("unroll") for (int k = 0; k < 2; ++k) dst[m][k] = *(const LAS bf16x8*)(lds + PG8_SA(b, h) + aoff + m * 2048 + k * 1024); } while (0)
; #define PG8_LDB(dst, b, h) do { _Pragma("unroll") for (int n = 0; n < 2; ++n) _Pragma("unroll") for (int k = 0; k < 2; ++k) dst[n][k] = *(const LAS bf16x8*)(lds + PG8_SB(b, h) + boff + n * 2048 + k * 1024); } while (0)
; #define PG8_MMA(ai, bj, At, Bt) do { __builtin_amdgcn_s_setprio(1); _Pragma("unroll") for (int m = 0; m < 4; ++m) _Pragma("unroll") for (int n = 0; n < 2; ++n) _Pragma("unroll") for (int k = 0; k < 2; ++k) \
;         acc[ai][bj][m][n] = __builtin_amdgcn_mfma_f32_16x16x32_bf16(Bt[n][k], At[m][k], acc[ai][bj][m][n], 0, 0, 0); __builtin_amdgcn_s_setprio(0); } while (0)
; #define PG8_WAIT_V(n) asm volatile("s_waitcnt vmcnt(" #n ")" ::: "memory")
; #define PG8_WAIT_L(n) asm volatile("s_waitcnt lgkmcnt(" #n ")" ::: "memory")
; #define PG8_BAR __builtin_amdgcn_s_barrier()
; template <class Epi, class Sched, bool ALIGN_EPI, bool SP2>
; __device__ __forceinline__ void gemm_phase(LAS unsigned char* lds, const Gemm g, const Sched& S, const Epi& E) {
;     ...
;         for (int t = 0; t < nt; t += 2) {
;             const bool last = (t == nt - 2);
;             const char* a1 = cA + (size_t)(t + 1) * kstep;
;             const char* a2 = last ? nA : cA + (size_t)(t + 2) * kstep; const char* b2 = last ? nB : cB + (size_t)(t + 2) * kstep;
;             const char* a3 = a2 + kstep; const char* b3 = b2 + kstep;
;             if constexpr (SP2) {
;             PG8_LDB(B0, 0, 0); PG8_LDB(B1, 0, 1); PG8_SCHED; PG8_LDA(At, 0, 0); PG8_STAGE(PG8_SA(1, 1), a1 + hstep, voffA);
;             PG8_WAIT_V(8); PG8_WAIT_L(0); PG8_BAR; PG8_MMA(0, 0, At, B0); PG8_MMA(0, 1, At, B1); PG8_BAR; PG8_SCHED;
;             PG8_LDA(At, 0, 1); PG8_STAGE(PG8_SB(0, 0), b2, voffB); PG8_STAGE(PG8_SB(0, 1), b2 + hstep, voffB); PG8_STAGE(PG8_SA(0, 0), a2, voffA);
;             PG8_WAIT_V(8); PG8_WAIT_L(0); PG8_BAR; PG8_MMA(1, 0, At, B0); PG8_MMA(1, 1, At, B1); PG8_BAR; PG8_SCHED;
.LBB0_468:
	v_add_u32_e32 v140, s62, v187
	v_add_u32_e32 v156, s63, v187
	s_add_i32 m0, s43, 0xc000
	s_nop 0
	global_load_lds_dwordx4 v176, s[28:29]
	s_add_i32 m0, s43, 0xe000
	s_nop 0
	global_load_lds_dwordx4 v178, s[28:29]
	ds_read_b128 v[128:131], v140
	ds_read_b128 v[132:135], v140 offset:1024
	ds_read_b128 v[136:139], v140 offset:2048
	ds_read_b128 v[140:143], v140 offset:3072
	ds_read_b128 v[144:147], v156
	ds_read_b128 v[148:151], v156 offset:1024
	ds_read_b128 v[152:155], v156 offset:2048
	ds_read_b128 v[156:159], v156 offset:3072
	ds_read_b128 v[160:163], v188
	ds_read_b128 v[190:193], v188 offset:1024
	ds_read_b128 v[194:197], v188 offset:2048
	ds_read_b128 v[198:201], v188 offset:3072
	ds_read_b128 v[202:205], v188 offset:4096
	ds_read_b128 v[206:209], v188 offset:5120
	ds_read_b128 v[210:213], v188 offset:6144
	ds_read_b128 v[214:217], v188 offset:7168
	s_add_u32 s34, s28, 0xfffe0080
	s_addc_u32 s35, s29, -1
	s_cmp_eq_u32 s58, 4
	s_cselect_b32 s37, s21, s35
	s_cselect_b32 s36, s50, s34
	s_cselect_b32 s35, s23, s57
	s_cselect_b32 s34, s51, s56
	s_waitcnt vmcnt(8)
	s_waitcnt lgkmcnt(0)
	s_barrier
	s_setprio 1
	s_waitcnt lgkmcnt(0)
	v_mfma_f32_16x16x32_bf16 v[124:127], v[128:131], v[160:163], v[124:127]
	v_mfma_f32_16x16x32_bf16 v[120:123], v[136:139], v[160:163], v[120:123]
	v_mfma_f32_16x16x32_bf16 v[116:119], v[128:131], v[194:197], v[116:119]
	v_mfma_f32_16x16x32_bf16 v[112:115], v[136:139], v[194:197], v[112:115]
	v_mfma_f32_16x16x32_bf16 v[108:111], v[128:131], v[202:205], v[108:111]
	v_mfma_f32_16x16x32_bf16 v[104:107], v[136:139], v[202:205], v[104:107]
	v_mfma_f32_16x16x32_bf16 v[100:103], v[128:131], v[210:213], v[100:103]
	v_mfma_f32_16x16x32_bf16 v[96:99], v[136:139], v[210:213], v[96:99]
	v_mfma_f32_16x16x32_bf16 v[124:127], v[132:135], v[190:193], v[124:127]
	v_mfma_f32_16x16x32_bf16 v[120:123], v[140:143], v[190:193], v[120:123]
	v_mfma_f32_16x16x32_bf16 v[116:119], v[132:135], v[198:201], v[116:119]
	v_mfma_f32_16x16x32_bf16 v[112:115], v[140:143], v[198:201], v[112:115]
	v_mfma_f32_16x16x32_bf16 v[108:111], v[132:135], v[206:209], v[108:111]
	v_mfma_f32_16x16x32_bf16 v[104:107], v[140:143], v[206:209], v[104:107]
	v_mfma_f32_16x16x32_bf16 v[100:103], v[132:135], v[214:217], v[100:103]
	v_mfma_f32_16x16x32_bf16 v[96:99], v[140:143], v[214:217], v[96:99]
	s_nop 0
	s_nop 0
	v_mfma_f32_16x16x32_bf16 v[92:95], v[144:147], v[160:163], v[92:95]
	v_mfma_f32_16x16x32_bf16 v[88:91], v[152:155], v[160:163], v[88:91]
	v_mfma_f32_16x16x32_bf16 v[84:87], v[144:147], v[194:197], v[84:87]
	v_mfma_f32_16x16x32_bf16 v[80:83], v[152:155], v[194:197], v[80:83]
	v_mfma_f32_16x16x32_bf16 v[76:79], v[144:147], v[202:205], v[76:79]
	v_mfma_f32_16x16x32_bf16 v[72:75], v[152:155], v[202:205], v[72:75]
	v_mfma_f32_16x16x32_bf16 v[68:71], v[144:147], v[210:213], v[68:71]
	v_mfma_f32_16x16x32_bf16 v[64:67], v[152:155], v[210:213], v[64:67]
	v_mfma_f32_16x16x32_bf16 v[92:95], v[148:151], v[190:193], v[92:95]
	v_mfma_f32_16x16x32_bf16 v[88:91], v[156:159], v[190:193], v[88:91]
	v_mfma_f32_16x16x32_bf16 v[84:87], v[148:151], v[198:201], v[84:87]
	v_mfma_f32_16x16x32_bf16 v[80:83], v[156:159], v[198:201], v[80:83]
	v_mfma_f32_16x16x32_bf16 v[76:79], v[148:151], v[206:209], v[76:79]
	v_mfma_f32_16x16x32_bf16 v[72:75], v[156:159], v[206:209], v[72:75]
	v_mfma_f32_16x16x32_bf16 v[68:71], v[148:151], v[214:217], v[68:71]
	v_mfma_f32_16x16x32_bf16 v[64:67], v[156:159], v[214:217], v[64:67]
	s_setprio 0
	s_barrier
	s_add_i32 s59, s62, s42
	s_mov_b32 m0, s59
	s_nop 0
	global_load_lds_dwordx4 v166, s[34:35]
	s_add_i32 m0, s59, 0x2000
	s_add_u32 s72, s34, 0x20000
	s_addc_u32 s73, s35, 0
	s_add_i32 s59, s63, s42
	global_load_lds_dwordx4 v170, s[34:35]
	s_mov_b32 m0, s59
	s_nop 0
	global_load_lds_dwordx4 v166, s[72:73]
	s_add_i32 m0, s59, 0x2000
	s_nop 0
	global_load_lds_dwordx4 v170, s[72:73]
	s_mov_b32 m0, s43
	s_nop 0
	global_load_lds_dwordx4 v164, s[36:37]
	s_mov_b32 m0, s44
	s_nop 0
	global_load_lds_dwordx4 v168, s[36:37]
	ds_read_b128 v[160:163], v188 offset:16384
	ds_read_b128 v[190:193], v188 offset:17408
	ds_read_b128 v[194:197], v188 offset:18432
	ds_read_b128 v[198:201], v188 offset:19456
	ds_read_b128 v[202:205], v188 offset:20480
	ds_read_b128 v[206:209], v188 offset:21504
	ds_read_b128 v[210:213], v188 offset:22528
	ds_read_b128 v[214:217], v188 offset:23552
	s_waitcnt vmcnt(8)
	s_waitcnt lgkmcnt(0)
	s_barrier
	s_setprio 1
	s_waitcnt lgkmcnt(0)
	v_mfma_f32_16x16x32_bf16 v[60:63], v[128:131], v[160:163], v[60:63]
	v_mfma_f32_16x16x32_bf16 v[56:59], v[136:139], v[160:163], v[56:59]
	v_mfma_f32_16x16x32_bf16 v[52:55], v[128:131], v[194:197], v[52:55]
	v_mfma_f32_16x16x32_bf16 v[48:51], v[136:139], v[194:197], v[48:51]
	v_mfma_f32_16x16x32_bf16 v[44:47], v[128:131], v[202:205], v[44:47]
	v_mfma_f32_16x16x32_bf16 v[40:43], v[136:139], v[202:205], v[40:43]
	v_mfma_f32_16x16x32_bf16 v[36:39], v[128:131], v[210:213], v[36:39]
	v_mfma_f32_16x16x32_bf16 v[32:35], v[136:139], v[210:213], v[32:35]
	v_mfma_f32_16x16x32_bf16 v[60:63], v[132:135], v[190:193], v[60:63]
	v_mfma_f32_16x16x32_bf16 v[56:59], v[140:143], v[190:193], v[56:59]
	v_mfma_f32_16x16x32_bf16 v[52:55], v[132:135], v[198:201], v[52:55]
	v_mfma_f32_16x16x32_bf16 v[48:51], v[140:143], v[198:201], v[48:51]
	v_mfma_f32_16x16x32_bf16 v[44:47], v[132:135], v[206:209], v[44:47]
	v_mfma_f32_16x16x32_bf16 v[40:43], v[140:143], v[206:209], v[40:43]
	v_mfma_f32_16x16x32_bf16 v[36:39], v[132:135], v[214:217], v[36:39]
	v_mfma_f32_16x16x32_bf16 v[32:35], v[140:143], v[214:217], v[32:35]
	s_nop 0
	s_nop 0
	v_mfma_f32_16x16x32_bf16 v[28:31], v[144:147], v[160:163], v[28:31]
	v_mfma_f32_16x16x32_bf16 v[24:27], v[152:155], v[160:163], v[24:27]
	v_mfma_f32_16x16x32_bf16 v[20:23], v[144:147], v[194:197], v[20:23]
	v_mfma_f32_16x16x32_bf16 v[16:19], v[152:155], v[194:197], v[16:19]
	v_mfma_f32_16x16x32_bf16 v[12:15], v[144:147], v[202:205], v[12:15]
	v_mfma_f32_16x16x32_bf16 v[8:11], v[152:155], v[202:205], v[8:11]
	v_mfma_f32_16x16x32_bf16 v[4:7], v[144:147], v[210:213], v[4:7]
	v_mfma_f32_16x16x32_bf16 v[0:3], v[152:155], v[210:213], v[0:3]
	v_mfma_f32_16x16x32_bf16 v[28:31], v[148:151], v[190:193], v[28:31]
	v_mfma_f32_16x16x32_bf16 v[24:27], v[156:159], v[190:193], v[24:27]
	v_mfma_f32_16x16x32_bf16 v[20:23], v[148:151], v[198:201], v[20:23]
	v_mfma_f32_16x16x32_bf16 v[16:19], v[156:159], v[198:201], v[16:19]
	v_mfma_f32_16x16x32_bf16 v[12:15], v[148:151], v[206:209], v[12:15]
	v_mfma_f32_16x16x32_bf16 v[8:11], v[156:159], v[206:209], v[8:11]
	v_mfma_f32_16x16x32_bf16 v[4:7], v[148:151], v[214:217], v[4:7]
	v_mfma_f32_16x16x32_bf16 v[0:3], v[156:159], v[214:217], v[0:3]
	s_setprio 0
	s_barrier
; #define PG8_STAGE(bufoff, gbase, voff) do { _Pragma("unroll") for (int _i = 0; _i < 2; ++_i) \
;         __builtin_amdgcn_global_load_lds((const unsigned*)((const char*)(gbase) + (voff)[_i]), (LAS unsigned*)(lds + (bufoff) + ldsw + _i * 8192), 16, 0, 0); } while (0)
; #define PG8_LDA(dst, b, h) do { _Pragma("unroll") for (int m = 0; m < 4; ++m) _Pragma("unroll") for (int k = 0; k < 2; ++k) dst[m][k] = *(const LAS bf16x8*)(lds + PG8_SA(b, h) + aoff + m * 2048 + k * 1024); } while (0)
; #define PG8_LDB(dst, b, h) do { _Pragma("unroll") for (int n = 0; n < 2; ++n) _Pragma("unroll") for (int k = 0; k < 2; ++k) dst[n][k] = *(const LAS bf16x8*)(lds + PG8_SB(b, h) + boff + n * 2048 + k * 1024); } while (0)
; #define PG8_MMA(ai, bj, At, Bt) do { __builtin_amdgcn_s_setprio(1); _Pragma("unroll") for (int m = 0; m < 4; ++m) _Pragma("unroll") for (int n = 0; n < 2; ++n) _Pragma("unroll") for (int k = 0; k < 2; ++k) \
;         acc[ai][bj][m][n] = __builtin_amdgcn_mfma_f32_16x16x32_bf16(Bt[n][k], At[m][k], acc[ai][bj][m][n], 0, 0, 0); __builtin_amdgcn_s_setprio(0); } while (0)
; #define PG8_WAIT_V(n) asm volatile("s_waitcnt vmcnt(" #n ")" ::: "memory")
; #define PG8_WAIT_L(n) asm volatile("s_waitcnt lgkmcnt(" #n ")" ::: "memory")
; #define PG8_BAR __builtin_amdgcn_s_barrier()
; #define PG8_SCHED __builtin_amdgcn_sched_barrier(0)
; template <class Epi, class Sched, bool ALIGN_EPI, bool SP2>
; __device__ __forceinline__ void gemm_phase(LAS unsigned char* lds, const Gemm g, const Sched& S, const Epi& E) {
;     ...
;             PG8_LDB(B0, 1, 0); PG8_LDB(B1, 1, 1); PG8_SCHED; PG8_LDA(At, 1, 0); PG8_STAGE(PG8_SA(0, 1), a2 + hstep, voffA);
;             PG8_WAIT_V(8); PG8_WAIT_L(0); PG8_BAR; PG8_MMA(0, 0, At, B0); PG8_MMA(0, 1, At, B1); PG8_BAR; PG8_SCHED;
;             PG8_LDA(At, 1, 1); PG8_STAGE(PG8_SB(1, 0), b3, voffB); PG8_STAGE(PG8_SB(1, 1), b3 + hstep, voffB); PG8_STAGE(PG8_SA(1, 0), a3, voffA);
;             PG8_WAIT_V(8); PG8_WAIT_L(0); PG8_BAR; PG8_MMA(1, 0, At, B0); PG8_MMA(1, 1, At, B1); PG8_BAR; PG8_SCHED;
	s_add_i32 s59, 0, 0x18000
	s_add_i32 s71, 0, 0x1c000
	v_add_u32_e32 v140, s59, v187
	v_add_u32_e32 v156, s71, v187
	s_add_u32 s36, s36, 0x20000
	s_addc_u32 s37, s37, 0
	s_mov_b32 m0, s45
	s_nop 0
	global_load_lds_dwordx4 v164, s[36:37]
	s_mov_b32 m0, s46
	s_nop 0
	global_load_lds_dwordx4 v168, s[36:37]
	ds_read_b128 v[128:131], v140
	ds_read_b128 v[132:135], v140 offset:1024
	ds_read_b128 v[136:139], v140 offset:2048
	ds_read_b128 v[140:143], v140 offset:3072
	ds_read_b128 v[144:147], v156
	ds_read_b128 v[148:151], v156 offset:1024
	ds_read_b128 v[152:155], v156 offset:2048
	ds_read_b128 v[156:159], v156 offset:3072
	ds_read_b128 v[160:163], v188 offset:32768
	ds_read_b128 v[190:193], v188 offset:33792
	ds_read_b128 v[194:197], v188 offset:34816
	ds_read_b128 v[198:201], v188 offset:35840
	ds_read_b128 v[202:205], v188 offset:36864
	ds_read_b128 v[206:209], v188 offset:37888
	ds_read_b128 v[210:213], v188 offset:38912
	ds_read_b128 v[214:217], v188 offset:39936
	s_waitcnt vmcnt(8)
	s_waitcnt lgkmcnt(0)
	s_barrier
	s_setprio 1
	s_waitcnt lgkmcnt(0)
	v_mfma_f32_16x16x32_bf16 v[124:127], v[128:131], v[160:163], v[124:127]
	v_mfma_f32_16x16x32_bf16 v[120:123], v[136:139], v[160:163], v[120:123]
	v_mfma_f32_16x16x32_bf16 v[116:119], v[128:131], v[194:197], v[116:119]
	v_mfma_f32_16x16x32_bf16 v[112:115], v[136:139], v[194:197], v[112:115]
	v_mfma_f32_16x16x32_bf16 v[108:111], v[128:131], v[202:205], v[108:111]
	v_mfma_f32_16x16x32_bf16 v[104:107], v[136:139], v[202:205], v[104:107]
	v_mfma_f32_16x16x32_bf16 v[100:103], v[128:131], v[210:213], v[100:103]
	v_mfma_f32_16x16x32_bf16 v[96:99], v[136:139], v[210:213], v[96:99]
	v_mfma_f32_16x16x32_bf16 v[124:127], v[132:135], v[190:193], v[124:127]
	v_mfma_f32_16x16x32_bf16 v[120:123], v[140:143], v[190:193], v[120:123]
	v_mfma_f32_16x16x32_bf16 v[116:119], v[132:135], v[198:201], v[116:119]
	v_mfma_f32_16x16x32_bf16 v[112:115], v[140:143], v[198:201], v[112:115]
	v_mfma_f32_16x16x32_bf16 v[108:111], v[132:135], v[206:209], v[108:111]
	v_mfma_f32_16x16x32_bf16 v[104:107], v[140:143], v[206:209], v[104:107]
	v_mfma_f32_16x16x32_bf16 v[100:103], v[132:135], v[214:217], v[100:103]
	v_mfma_f32_16x16x32_bf16 v[96:99], v[140:143], v[214:217], v[96:99]
	s_nop 0
	s_nop 0
	v_mfma_f32_16x16x32_bf16 v[92:95], v[144:147], v[160:163], v[92:95]
	v_mfma_f32_16x16x32_bf16 v[88:91], v[152:155], v[160:163], v[88:91]
	v_mfma_f32_16x16x32_bf16 v[84:87], v[144:147], v[194:197], v[84:87]
	v_mfma_f32_16x16x32_bf16 v[80:83], v[152:155], v[194:197], v[80:83]
	v_mfma_f32_16x16x32_bf16 v[76:79], v[144:147], v[202:205], v[76:79]
	v_mfma_f32_16x16x32_bf16 v[72:75], v[152:155], v[202:205], v[72:75]
	v_mfma_f32_16x16x32_bf16 v[68:71], v[144:147], v[210:213], v[68:71]
	v_mfma_f32_16x16x32_bf16 v[64:67], v[152:155], v[210:213], v[64:67]
	v_mfma_f32_16x16x32_bf16 v[92:95], v[148:151], v[190:193], v[92:95]
	v_mfma_f32_16x16x32_bf16 v[88:91], v[156:159], v[190:193], v[88:91]
	v_mfma_f32_16x16x32_bf16 v[84:87], v[148:151], v[198:201], v[84:87]
	v_mfma_f32_16x16x32_bf16 v[80:83], v[156:159], v[198:201], v[80:83]
	v_mfma_f32_16x16x32_bf16 v[76:79], v[148:151], v[206:209], v[76:79]
	v_mfma_f32_16x16x32_bf16 v[72:75], v[156:159], v[206:209], v[72:75]
	v_mfma_f32_16x16x32_bf16 v[68:71], v[148:151], v[214:217], v[68:71]
	v_mfma_f32_16x16x32_bf16 v[64:67], v[156:159], v[214:217], v[64:67]
	s_setprio 0
	s_barrier
	s_add_u32 s100, s36, 0xfffe0080
	s_addc_u32 s101, s37, -1
	s_add_u32 s98, s34, 0x80
	s_addc_u32 s99, s35, 0
	s_add_i32 s36, s59, s42
	s_mov_b32 m0, s36
	s_nop 0
	global_load_lds_dwordx4 v166, s[98:99]
	s_add_i32 m0, s36, 0x2000
	s_add_u32 s34, s34, 0x20080
	s_addc_u32 s35, s35, 0
	s_add_i32 s36, s71, s42
	global_load_lds_dwordx4 v170, s[98:99]
	s_mov_b32 m0, s36
	s_nop 0
	global_load_lds_dwordx4 v166, s[34:35]
	s_add_i32 m0, s36, 0x2000
	s_nop 0
	global_load_lds_dwordx4 v170, s[34:35]
	s_mov_b32 m0, s54
	s_nop 0
	global_load_lds_dwordx4 v164, s[100:101]
	s_mov_b32 m0, s55
	s_nop 0
	global_load_lds_dwordx4 v168, s[100:101]
	ds_read_b128 v[160:163], v188 offset:49152
	ds_read_b128 v[190:193], v188 offset:50176
	ds_read_b128 v[194:197], v188 offset:51200
	ds_read_b128 v[198:201], v188 offset:52224
	ds_read_b128 v[202:205], v188 offset:53248
	ds_read_b128 v[206:209], v188 offset:54272
	ds_read_b128 v[210:213], v188 offset:55296
	ds_read_b128 v[214:217], v188 offset:56320
	s_waitcnt vmcnt(8)
	s_waitcnt lgkmcnt(0)
	s_barrier
	s_setprio 1
	s_waitcnt lgkmcnt(0)
	v_mfma_f32_16x16x32_bf16 v[60:63], v[128:131], v[160:163], v[60:63]
	v_mfma_f32_16x16x32_bf16 v[56:59], v[136:139], v[160:163], v[56:59]
	v_mfma_f32_16x16x32_bf16 v[52:55], v[128:131], v[194:197], v[52:55]
	v_mfma_f32_16x16x32_bf16 v[48:51], v[136:139], v[194:197], v[48:51]
	v_mfma_f32_16x16x32_bf16 v[44:47], v[128:131], v[202:205], v[44:47]
	v_mfma_f32_16x16x32_bf16 v[40:43], v[136:139], v[202:205], v[40:43]
	v_mfma_f32_16x16x32_bf16 v[36:39], v[128:131], v[210:213], v[36:39]
	v_mfma_f32_16x16x32_bf16 v[32:35], v[136:139], v[210:213], v[32:35]
	v_mfma_f32_16x16x32_bf16 v[60:63], v[132:135], v[190:193], v[60:63]
	v_mfma_f32_16x16x32_bf16 v[56:59], v[140:143], v[190:193], v[56:59]
	v_mfma_f32_16x16x32_bf16 v[52:55], v[132:135], v[198:201], v[52:55]
	v_mfma_f32_16x16x32_bf16 v[48:51], v[140:143], v[198:201], v[48:51]
	v_mfma_f32_16x16x32_bf16 v[44:47], v[132:135], v[206:209], v[44:47]
	v_mfma_f32_16x16x32_bf16 v[40:43], v[140:143], v[206:209], v[40:43]
	v_mfma_f32_16x16x32_bf16 v[36:39], v[132:135], v[214:217], v[36:39]
	v_mfma_f32_16x16x32_bf16 v[32:35], v[140:143], v[214:217], v[32:35]
	s_nop 0
	s_nop 0
	v_mfma_f32_16x16x32_bf16 v[28:31], v[144:147], v[160:163], v[28:31]
	v_mfma_f32_16x16x32_bf16 v[24:27], v[152:155], v[160:163], v[24:27]
	v_mfma_f32_16x16x32_bf16 v[20:23], v[144:147], v[194:197], v[20:23]
	v_mfma_f32_16x16x32_bf16 v[16:19], v[152:155], v[194:197], v[16:19]
	v_mfma_f32_16x16x32_bf16 v[12:15], v[144:147], v[202:205], v[12:15]
	v_mfma_f32_16x16x32_bf16 v[8:11], v[152:155], v[202:205], v[8:11]
	v_mfma_f32_16x16x32_bf16 v[4:7], v[144:147], v[210:213], v[4:7]
	v_mfma_f32_16x16x32_bf16 v[0:3], v[152:155], v[210:213], v[0:3]
	v_mfma_f32_16x16x32_bf16 v[28:31], v[148:151], v[190:193], v[28:31]
	v_mfma_f32_16x16x32_bf16 v[24:27], v[156:159], v[190:193], v[24:27]
	v_mfma_f32_16x16x32_bf16 v[20:23], v[148:151], v[198:201], v[20:23]
	v_mfma_f32_16x16x32_bf16 v[16:19], v[156:159], v[198:201], v[16:19]
	v_mfma_f32_16x16x32_bf16 v[12:15], v[148:151], v[206:209], v[12:15]
	v_mfma_f32_16x16x32_bf16 v[8:11], v[156:159], v[206:209], v[8:11]
	v_mfma_f32_16x16x32_bf16 v[4:7], v[148:151], v[214:217], v[4:7]
	v_mfma_f32_16x16x32_bf16 v[0:3], v[156:159], v[214:217], v[0:3]
	s_setprio 0
	s_barrier
	s_add_i32 s58, s58, 2
	s_add_u32 s28, s28, 0x100
	s_addc_u32 s29, s29, 0
	s_add_u32 s56, s56, 0x100
	s_addc_u32 s57, s57, 0
	s_cmp_gt_u32 s58, 5
	s_cbranch_scc0 .LBB0_468
	s_and_b64 vcc, exec, s[18:19]
	s_cbranch_vccz .LBB0_471
	s_barrier

; #define PG8_STAGE(bufoff, gbase, voff) do { _Pragma("unroll") for (int _i = 0; _i < 2; ++_i) \
;         __builtin_amdgcn_global_load_lds((const unsigned*)((const char*)(gbase) + (voff)[_i]), (LAS unsigned*)(lds + (bufoff) + ldsw + _i * 8192), 16, 0, 0); } while (0)
; #define PG8_LDA(dst, b, h) do { _Pragma("unroll") for (int m = 0; m < 4; ++m) _Pragma("unroll") for (int k = 0; k < 2; ++k) dst[m][k] = *(const LAS bf16x8*)(lds + PG8_SA(b, h) + aoff + m * 2048 + k * 1024); } while (0)
; #define PG8_LDB(dst, b, h) do { _Pragma("unroll") for (int n = 0; n < 2; ++n) _Pragma("unroll") for (int k = 0; k < 2; ++k) dst[n][k] = *(const LAS bf16x8*)(lds + PG8_SB(b, h) + boff + n * 2048 + k * 1024); } while (0)
; #define PG8_MMA(ai, bj, At, Bt) do { __builtin_amdgcn_s_setprio(1); _Pragma("unroll") for (int m = 0; m < 4; ++m) _Pragma("unroll") for (int n = 0; n < 2; ++n) _Pragma("unroll") for (int k = 0; k < 2; ++k) \
;         acc[ai][bj][m][n] = __builtin_amdgcn_mfma_f32_16x16x32_bf16(Bt[n][k], At[m][k], acc[ai][bj][m][n], 0, 0, 0); __builtin_amdgcn_s_setprio(0); } while (0)
; #define PG8_WAIT_V(n) asm volatile("s_waitcnt vmcnt(" #n ")" ::: "memory")
; #define PG8_WAIT_L(n) asm volatile("s_waitcnt lgkmcnt(" #n ")" ::: "memory")
; #define PG8_BAR __builtin_amdgcn_s_barrier()
; template <class Epi, class Sched, bool ALIGN_EPI, bool SP2>
; __device__ __forceinline__ void gemm_phase(LAS unsigned char* lds, const Gemm g, const Sched& S, const Epi& E) {
;     ...
;         for (int t = 0; t < nt; t += 2) {
;             const bool last = (t == nt - 2);
;             const char* a1 = cA + (size_t)(t + 1) * kstep;
;             const char* a2 = last ? nA : cA + (size_t)(t + 2) * kstep; const char* b2 = last ? nB : cB + (size_t)(t + 2) * kstep;
;             const char* a3 = a2 + kstep; const char* b3 = b2 + kstep;
;             if constexpr (SP2) {
;             PG8_LDB(B0, 0, 0); PG8_LDB(B1, 0, 1); PG8_SCHED; PG8_LDA(At, 0, 0); PG8_STAGE(PG8_SA(1, 1), a1 + hstep, voffA);
;             PG8_WAIT_V(8); PG8_WAIT_L(0); PG8_BAR; PG8_MMA(0, 0, At, B0); PG8_MMA(0, 1, At, B1); PG8_BAR; PG8_SCHED;
;             PG8_LDA(At, 0, 1); PG8_STAGE(PG8_SB(0, 0), b2, voffB); PG8_STAGE(PG8_SB(0, 1), b2 + hstep, voffB); PG8_STAGE(PG8_SA(0, 0), a2, voffA);
;             PG8_WAIT_V(8); PG8_WAIT_L(0); PG8_BAR; PG8_MMA(1, 0, At, B0); PG8_MMA(1, 1, At, B1); PG8_BAR; PG8_SCHED;
.LBB0_683:
	s_add_i32 m0, s23, 0xc000
	s_nop 0
	global_load_lds_dwordx4 v136, s[24:25]
	s_add_i32 m0, s23, 0xe000
	s_nop 0
	global_load_lds_dwordx4 v138, s[24:25]
	ds_read_b128 v[150:153], v147
	ds_read_b128 v[154:157], v147 offset:1024
	ds_read_b128 v[158:161], v147 offset:2048
	ds_read_b128 v[162:165], v147 offset:3072
	ds_read_b128 v[166:169], v148
	ds_read_b128 v[170:173], v148 offset:1024
	ds_read_b128 v[176:179], v148 offset:2048
	ds_read_b128 v[180:183], v148 offset:3072
	ds_read_b128 v[184:187], v149
	ds_read_b128 v[188:191], v149 offset:1024
	ds_read_b128 v[192:195], v149 offset:2048
	ds_read_b128 v[196:199], v149 offset:3072
	ds_read_b128 v[200:203], v149 offset:4096
	ds_read_b128 v[204:207], v149 offset:5120
	ds_read_b128 v[208:211], v149 offset:6144
	ds_read_b128 v[212:215], v149 offset:7168
	s_add_u32 s26, s24, 0xfffc0080
	s_addc_u32 s27, s25, -1
	s_cmp_eq_u32 s52, 12
	s_cselect_b32 s29, s15, s27
	s_cselect_b32 s28, s48, s26
	s_cselect_b32 s27, s17, s51
	s_cselect_b32 s26, s49, s50
	s_waitcnt vmcnt(8)
	s_waitcnt lgkmcnt(0)
	s_barrier
	s_setprio 1
	s_waitcnt lgkmcnt(0)
	v_mfma_f32_16x16x32_bf16 v[124:127], v[150:153], v[184:187], v[124:127]
	v_mfma_f32_16x16x32_bf16 v[120:123], v[158:161], v[184:187], v[120:123]
	v_mfma_f32_16x16x32_bf16 v[108:111], v[150:153], v[192:195], v[108:111]
	v_mfma_f32_16x16x32_bf16 v[104:107], v[158:161], v[192:195], v[104:107]
	v_mfma_f32_16x16x32_bf16 v[92:95], v[150:153], v[200:203], v[92:95]
	v_mfma_f32_16x16x32_bf16 v[88:91], v[158:161], v[200:203], v[88:91]
	v_mfma_f32_16x16x32_bf16 v[76:79], v[150:153], v[208:211], v[76:79]
	v_mfma_f32_16x16x32_bf16 v[72:75], v[158:161], v[208:211], v[72:75]
	v_mfma_f32_16x16x32_bf16 v[124:127], v[154:157], v[188:191], v[124:127]
	v_mfma_f32_16x16x32_bf16 v[120:123], v[162:165], v[188:191], v[120:123]
	v_mfma_f32_16x16x32_bf16 v[108:111], v[154:157], v[196:199], v[108:111]
	v_mfma_f32_16x16x32_bf16 v[104:107], v[162:165], v[196:199], v[104:107]
	v_mfma_f32_16x16x32_bf16 v[92:95], v[154:157], v[204:207], v[92:95]
	v_mfma_f32_16x16x32_bf16 v[88:91], v[162:165], v[204:207], v[88:91]
	v_mfma_f32_16x16x32_bf16 v[76:79], v[154:157], v[212:215], v[76:79]
	v_mfma_f32_16x16x32_bf16 v[72:75], v[162:165], v[212:215], v[72:75]
	s_nop 0
	s_nop 0
	v_mfma_f32_16x16x32_bf16 v[116:119], v[166:169], v[184:187], v[116:119]
	v_mfma_f32_16x16x32_bf16 v[112:115], v[176:179], v[184:187], v[112:115]
	v_mfma_f32_16x16x32_bf16 v[100:103], v[166:169], v[192:195], v[100:103]
	v_mfma_f32_16x16x32_bf16 v[96:99], v[176:179], v[192:195], v[96:99]
	v_mfma_f32_16x16x32_bf16 v[84:87], v[166:169], v[200:203], v[84:87]
	v_mfma_f32_16x16x32_bf16 v[80:83], v[176:179], v[200:203], v[80:83]
	v_mfma_f32_16x16x32_bf16 v[68:71], v[166:169], v[208:211], v[68:71]
	v_mfma_f32_16x16x32_bf16 v[64:67], v[176:179], v[208:211], v[64:67]
	v_mfma_f32_16x16x32_bf16 v[116:119], v[170:173], v[188:191], v[116:119]
	v_mfma_f32_16x16x32_bf16 v[112:115], v[180:183], v[188:191], v[112:115]
	v_mfma_f32_16x16x32_bf16 v[100:103], v[170:173], v[196:199], v[100:103]
	v_mfma_f32_16x16x32_bf16 v[96:99], v[180:183], v[196:199], v[96:99]
	v_mfma_f32_16x16x32_bf16 v[84:87], v[170:173], v[204:207], v[84:87]
	v_mfma_f32_16x16x32_bf16 v[80:83], v[180:183], v[204:207], v[80:83]
	v_mfma_f32_16x16x32_bf16 v[68:71], v[170:173], v[212:215], v[68:71]
	v_mfma_f32_16x16x32_bf16 v[64:67], v[180:183], v[212:215], v[64:67]
	s_setprio 0
	s_barrier
	s_add_i32 s53, s44, s30
	s_mov_b32 m0, s53
	s_nop 0
	global_load_lds_dwordx4 v132, s[26:27]
	s_add_i32 m0, s53, 0x2000
	s_add_u32 s54, s26, 0x40000
	s_addc_u32 s55, s27, 0
	s_add_i32 s53, s45, s30
	global_load_lds_dwordx4 v128, s[26:27]
	s_mov_b32 m0, s53
	s_nop 0
	global_load_lds_dwordx4 v132, s[54:55]
	s_add_i32 m0, s53, 0x2000
	s_nop 0
	global_load_lds_dwordx4 v128, s[54:55]
	s_mov_b32 m0, s23
	s_nop 0
	global_load_lds_dwordx4 v134, s[28:29]
	s_mov_b32 m0, s34
	s_nop 0
	global_load_lds_dwordx4 v130, s[28:29]
	ds_read_b128 v[184:187], v149 offset:16384
	ds_read_b128 v[188:191], v149 offset:17408
	ds_read_b128 v[192:195], v149 offset:18432
	ds_read_b128 v[196:199], v149 offset:19456
	ds_read_b128 v[200:203], v149 offset:20480
	ds_read_b128 v[204:207], v149 offset:21504
	ds_read_b128 v[208:211], v149 offset:22528
	ds_read_b128 v[212:215], v149 offset:23552
	s_waitcnt vmcnt(8)
	s_waitcnt lgkmcnt(0)
	s_barrier
	s_setprio 1
	s_waitcnt lgkmcnt(0)
	v_mfma_f32_16x16x32_bf16 v[60:63], v[150:153], v[184:187], v[60:63]
	v_mfma_f32_16x16x32_bf16 v[56:59], v[158:161], v[184:187], v[56:59]
	v_mfma_f32_16x16x32_bf16 v[44:47], v[150:153], v[192:195], v[44:47]
	v_mfma_f32_16x16x32_bf16 v[40:43], v[158:161], v[192:195], v[40:43]
	v_mfma_f32_16x16x32_bf16 v[28:31], v[150:153], v[200:203], v[28:31]
	v_mfma_f32_16x16x32_bf16 v[24:27], v[158:161], v[200:203], v[24:27]
	v_mfma_f32_16x16x32_bf16 v[12:15], v[150:153], v[208:211], v[12:15]
	v_mfma_f32_16x16x32_bf16 v[8:11], v[158:161], v[208:211], v[8:11]
	v_mfma_f32_16x16x32_bf16 v[60:63], v[154:157], v[188:191], v[60:63]
	v_mfma_f32_16x16x32_bf16 v[56:59], v[162:165], v[188:191], v[56:59]
	v_mfma_f32_16x16x32_bf16 v[44:47], v[154:157], v[196:199], v[44:47]
	v_mfma_f32_16x16x32_bf16 v[40:43], v[162:165], v[196:199], v[40:43]
	v_mfma_f32_16x16x32_bf16 v[28:31], v[154:157], v[204:207], v[28:31]
	v_mfma_f32_16x16x32_bf16 v[24:27], v[162:165], v[204:207], v[24:27]
	v_mfma_f32_16x16x32_bf16 v[12:15], v[154:157], v[212:215], v[12:15]
	v_mfma_f32_16x16x32_bf16 v[8:11], v[162:165], v[212:215], v[8:11]
	s_nop 0
	s_nop 0
	v_mfma_f32_16x16x32_bf16 v[52:55], v[166:169], v[184:187], v[52:55]
	v_mfma_f32_16x16x32_bf16 v[48:51], v[176:179], v[184:187], v[48:51]
	v_mfma_f32_16x16x32_bf16 v[36:39], v[166:169], v[192:195], v[36:39]
	v_mfma_f32_16x16x32_bf16 v[32:35], v[176:179], v[192:195], v[32:35]
	v_mfma_f32_16x16x32_bf16 v[20:23], v[166:169], v[200:203], v[20:23]
	v_mfma_f32_16x16x32_bf16 v[16:19], v[176:179], v[200:203], v[16:19]
	v_mfma_f32_16x16x32_bf16 v[4:7], v[166:169], v[208:211], v[4:7]
	v_mfma_f32_16x16x32_bf16 v[0:3], v[176:179], v[208:211], v[0:3]
	v_mfma_f32_16x16x32_bf16 v[52:55], v[170:173], v[188:191], v[52:55]
	v_mfma_f32_16x16x32_bf16 v[48:51], v[180:183], v[188:191], v[48:51]
	v_mfma_f32_16x16x32_bf16 v[36:39], v[170:173], v[196:199], v[36:39]
	v_mfma_f32_16x16x32_bf16 v[32:35], v[180:183], v[196:199], v[32:35]
	v_mfma_f32_16x16x32_bf16 v[20:23], v[170:173], v[204:207], v[20:23]
	v_mfma_f32_16x16x32_bf16 v[16:19], v[180:183], v[204:207], v[16:19]
	v_mfma_f32_16x16x32_bf16 v[4:7], v[170:173], v[212:215], v[4:7]
	v_mfma_f32_16x16x32_bf16 v[0:3], v[180:183], v[212:215], v[0:3]
	s_setprio 0
	s_barrier
; #define PG8_STAGE(bufoff, gbase, voff) do { _Pragma("unroll") for (int _i = 0; _i < 2; ++_i) \
;         __builtin_amdgcn_global_load_lds((const unsigned*)((const char*)(gbase) + (voff)[_i]), (LAS unsigned*)(lds + (bufoff) + ldsw + _i * 8192), 16, 0, 0); } while (0)
; #define PG8_LDA(dst, b, h) do { _Pragma("unroll") for (int m = 0; m < 4; ++m) _Pragma("unroll") for (int k = 0; k < 2; ++k) dst[m][k] = *(const LAS bf16x8*)(lds + PG8_SA(b, h) + aoff + m * 2048 + k * 1024); } while (0)
; #define PG8_LDB(dst, b, h) do { _Pragma("unroll") for (int n = 0; n < 2; ++n) _Pragma("unroll") for (int k = 0; k < 2; ++k) dst[n][k] = *(const LAS bf16x8*)(lds + PG8_SB(b, h) + boff + n * 2048 + k * 1024); } while (0)
; #define PG8_MMA(ai, bj, At, Bt) do { __builtin_amdgcn_s_setprio(1); _Pragma("unroll") for (int m = 0; m < 4; ++m) _Pragma("unroll") for (int n = 0; n < 2; ++n) _Pragma("unroll") for (int k = 0; k < 2; ++k) \
;         acc[ai][bj][m][n] = __builtin_amdgcn_mfma_f32_16x16x32_bf16(Bt[n][k], At[m][k], acc[ai][bj][m][n], 0, 0, 0); __builtin_amdgcn_s_setprio(0); } while (0)
; #define PG8_WAIT_V(n) asm volatile("s_waitcnt vmcnt(" #n ")" ::: "memory")
; #define PG8_WAIT_L(n) asm volatile("s_waitcnt lgkmcnt(" #n ")" ::: "memory")
; #define PG8_BAR __builtin_amdgcn_s_barrier()
; #define PG8_SCHED __builtin_amdgcn_sched_barrier(0)
; template <class Epi, class Sched, bool ALIGN_EPI, bool SP2>
; __device__ __forceinline__ void gemm_phase(LAS unsigned char* lds, const Gemm g, const Sched& S, const Epi& E) {
;     ...
;             PG8_LDB(B0, 1, 0); PG8_LDB(B1, 1, 1); PG8_SCHED; PG8_LDA(At, 1, 0); PG8_STAGE(PG8_SA(0, 1), a2 + hstep, voffA);
;             PG8_WAIT_V(8); PG8_WAIT_L(0); PG8_BAR; PG8_MMA(0, 0, At, B0); PG8_MMA(0, 1, At, B1); PG8_BAR; PG8_SCHED;
;             PG8_LDA(At, 1, 1); PG8_STAGE(PG8_SB(1, 0), b3, voffB); PG8_STAGE(PG8_SB(1, 1), b3 + hstep, voffB); PG8_STAGE(PG8_SA(1, 0), a3, voffA);
;             PG8_WAIT_V(8); PG8_WAIT_L(0); PG8_BAR; PG8_MMA(1, 0, At, B0); PG8_MMA(1, 1, At, B1); PG8_BAR; PG8_SCHED;
	s_add_i32 s53, 0, 0x18000
	s_add_i32 s54, 0, 0x1c000
	v_add_u32_e32 v162, s53, v145
	v_add_u32_e32 v174, s54, v145
	s_add_u32 s28, s28, 0x40000
	s_addc_u32 s29, s29, 0
	s_mov_b32 m0, s35
	s_nop 0
	global_load_lds_dwordx4 v134, s[28:29]
	s_mov_b32 m0, s36
	s_nop 0
	global_load_lds_dwordx4 v130, s[28:29]
	ds_read_b128 v[150:153], v162
	ds_read_b128 v[154:157], v162 offset:1024
	ds_read_b128 v[158:161], v162 offset:2048
	ds_read_b128 v[162:165], v162 offset:3072
	ds_read_b128 v[166:169], v174
	ds_read_b128 v[170:173], v174 offset:1024
	ds_read_b128 v[176:179], v174 offset:2048
	ds_read_b128 v[180:183], v174 offset:3072
	ds_read_b128 v[184:187], v149 offset:32768
	ds_read_b128 v[188:191], v149 offset:33792
	ds_read_b128 v[192:195], v149 offset:34816
	ds_read_b128 v[196:199], v149 offset:35840
	ds_read_b128 v[200:203], v149 offset:36864
	ds_read_b128 v[204:207], v149 offset:37888
	ds_read_b128 v[208:211], v149 offset:38912
	ds_read_b128 v[212:215], v149 offset:39936
	s_waitcnt vmcnt(8)
	s_waitcnt lgkmcnt(0)
	s_barrier
	s_setprio 1
	s_waitcnt lgkmcnt(0)
	v_mfma_f32_16x16x32_bf16 v[124:127], v[150:153], v[184:187], v[124:127]
	v_mfma_f32_16x16x32_bf16 v[120:123], v[158:161], v[184:187], v[120:123]
	v_mfma_f32_16x16x32_bf16 v[108:111], v[150:153], v[192:195], v[108:111]
	v_mfma_f32_16x16x32_bf16 v[104:107], v[158:161], v[192:195], v[104:107]
	v_mfma_f32_16x16x32_bf16 v[92:95], v[150:153], v[200:203], v[92:95]
	v_mfma_f32_16x16x32_bf16 v[88:91], v[158:161], v[200:203], v[88:91]
	v_mfma_f32_16x16x32_bf16 v[76:79], v[150:153], v[208:211], v[76:79]
	v_mfma_f32_16x16x32_bf16 v[72:75], v[158:161], v[208:211], v[72:75]
	v_mfma_f32_16x16x32_bf16 v[124:127], v[154:157], v[188:191], v[124:127]
	v_mfma_f32_16x16x32_bf16 v[120:123], v[162:165], v[188:191], v[120:123]
	v_mfma_f32_16x16x32_bf16 v[108:111], v[154:157], v[196:199], v[108:111]
	v_mfma_f32_16x16x32_bf16 v[104:107], v[162:165], v[196:199], v[104:107]
	v_mfma_f32_16x16x32_bf16 v[92:95], v[154:157], v[204:207], v[92:95]
	v_mfma_f32_16x16x32_bf16 v[88:91], v[162:165], v[204:207], v[88:91]
	v_mfma_f32_16x16x32_bf16 v[76:79], v[154:157], v[212:215], v[76:79]
	v_mfma_f32_16x16x32_bf16 v[72:75], v[162:165], v[212:215], v[72:75]
	s_nop 0
	s_nop 0
	v_mfma_f32_16x16x32_bf16 v[116:119], v[166:169], v[184:187], v[116:119]
	v_mfma_f32_16x16x32_bf16 v[112:115], v[176:179], v[184:187], v[112:115]
	v_mfma_f32_16x16x32_bf16 v[100:103], v[166:169], v[192:195], v[100:103]
	v_mfma_f32_16x16x32_bf16 v[96:99], v[176:179], v[192:195], v[96:99]
	v_mfma_f32_16x16x32_bf16 v[84:87], v[166:169], v[200:203], v[84:87]
	v_mfma_f32_16x16x32_bf16 v[80:83], v[176:179], v[200:203], v[80:83]
	v_mfma_f32_16x16x32_bf16 v[68:71], v[166:169], v[208:211], v[68:71]
	v_mfma_f32_16x16x32_bf16 v[64:67], v[176:179], v[208:211], v[64:67]
	v_mfma_f32_16x16x32_bf16 v[116:119], v[170:173], v[188:191], v[116:119]
	v_mfma_f32_16x16x32_bf16 v[112:115], v[180:183], v[188:191], v[112:115]
	v_mfma_f32_16x16x32_bf16 v[100:103], v[170:173], v[196:199], v[100:103]
	v_mfma_f32_16x16x32_bf16 v[96:99], v[180:183], v[196:199], v[96:99]
	v_mfma_f32_16x16x32_bf16 v[84:87], v[170:173], v[204:207], v[84:87]
	v_mfma_f32_16x16x32_bf16 v[80:83], v[180:183], v[204:207], v[80:83]
	v_mfma_f32_16x16x32_bf16 v[68:71], v[170:173], v[212:215], v[68:71]
	v_mfma_f32_16x16x32_bf16 v[64:67], v[180:183], v[212:215], v[64:67]
	s_setprio 0
	s_barrier
	s_add_u32 s100, s28, 0xfffc0080
	s_addc_u32 s101, s29, -1
	s_add_u32 s98, s26, 0x80
	s_addc_u32 s99, s27, 0
	s_add_i32 s28, s53, s30
	s_mov_b32 m0, s28
	s_nop 0
	global_load_lds_dwordx4 v132, s[98:99]
	s_add_i32 m0, s28, 0x2000
	s_add_u32 s26, s26, 0x40080
	s_addc_u32 s27, s27, 0
	s_add_i32 s28, s54, s30
	global_load_lds_dwordx4 v128, s[98:99]
	s_mov_b32 m0, s28
	s_nop 0
	global_load_lds_dwordx4 v132, s[26:27]
	s_add_i32 m0, s28, 0x2000
	s_nop 0
	global_load_lds_dwordx4 v128, s[26:27]
	s_mov_b32 m0, s38
	s_nop 0
	global_load_lds_dwordx4 v134, s[100:101]
	s_mov_b32 m0, s39
	s_nop 0
	global_load_lds_dwordx4 v130, s[100:101]
	ds_read_b128 v[184:187], v149 offset:49152
	ds_read_b128 v[188:191], v149 offset:50176
	ds_read_b128 v[192:195], v149 offset:51200
	ds_read_b128 v[196:199], v149 offset:52224
	ds_read_b128 v[200:203], v149 offset:53248
	ds_read_b128 v[204:207], v149 offset:54272
	ds_read_b128 v[208:211], v149 offset:55296
	ds_read_b128 v[212:215], v149 offset:56320
	s_waitcnt vmcnt(8)
	s_waitcnt lgkmcnt(0)
	s_barrier
	s_setprio 1
	s_waitcnt lgkmcnt(0)
	v_mfma_f32_16x16x32_bf16 v[60:63], v[150:153], v[184:187], v[60:63]
	v_mfma_f32_16x16x32_bf16 v[56:59], v[158:161], v[184:187], v[56:59]
	v_mfma_f32_16x16x32_bf16 v[44:47], v[150:153], v[192:195], v[44:47]
	v_mfma_f32_16x16x32_bf16 v[40:43], v[158:161], v[192:195], v[40:43]
	v_mfma_f32_16x16x32_bf16 v[28:31], v[150:153], v[200:203], v[28:31]
	v_mfma_f32_16x16x32_bf16 v[24:27], v[158:161], v[200:203], v[24:27]
	v_mfma_f32_16x16x32_bf16 v[12:15], v[150:153], v[208:211], v[12:15]
	v_mfma_f32_16x16x32_bf16 v[8:11], v[158:161], v[208:211], v[8:11]
	v_mfma_f32_16x16x32_bf16 v[60:63], v[154:157], v[188:191], v[60:63]
	v_mfma_f32_16x16x32_bf16 v[56:59], v[162:165], v[188:191], v[56:59]
	v_mfma_f32_16x16x32_bf16 v[44:47], v[154:157], v[196:199], v[44:47]
	v_mfma_f32_16x16x32_bf16 v[40:43], v[162:165], v[196:199], v[40:43]
	v_mfma_f32_16x16x32_bf16 v[28:31], v[154:157], v[204:207], v[28:31]
	v_mfma_f32_16x16x32_bf16 v[24:27], v[162:165], v[204:207], v[24:27]
	v_mfma_f32_16x16x32_bf16 v[12:15], v[154:157], v[212:215], v[12:15]
	v_mfma_f32_16x16x32_bf16 v[8:11], v[162:165], v[212:215], v[8:11]
	s_nop 0
	s_nop 0
	v_mfma_f32_16x16x32_bf16 v[52:55], v[166:169], v[184:187], v[52:55]
	v_mfma_f32_16x16x32_bf16 v[48:51], v[176:179], v[184:187], v[48:51]
	v_mfma_f32_16x16x32_bf16 v[36:39], v[166:169], v[192:195], v[36:39]
	v_mfma_f32_16x16x32_bf16 v[32:35], v[176:179], v[192:195], v[32:35]
	v_mfma_f32_16x16x32_bf16 v[20:23], v[166:169], v[200:203], v[20:23]
	v_mfma_f32_16x16x32_bf16 v[16:19], v[176:179], v[200:203], v[16:19]
	v_mfma_f32_16x16x32_bf16 v[4:7], v[166:169], v[208:211], v[4:7]
	v_mfma_f32_16x16x32_bf16 v[0:3], v[176:179], v[208:211], v[0:3]
	v_mfma_f32_16x16x32_bf16 v[52:55], v[170:173], v[188:191], v[52:55]
	v_mfma_f32_16x16x32_bf16 v[48:51], v[180:183], v[188:191], v[48:51]
	v_mfma_f32_16x16x32_bf16 v[36:39], v[170:173], v[196:199], v[36:39]
	v_mfma_f32_16x16x32_bf16 v[32:35], v[180:183], v[196:199], v[32:35]
	v_mfma_f32_16x16x32_bf16 v[20:23], v[170:173], v[204:207], v[20:23]
	v_mfma_f32_16x16x32_bf16 v[16:19], v[180:183], v[204:207], v[16:19]
	v_mfma_f32_16x16x32_bf16 v[4:7], v[170:173], v[212:215], v[4:7]
	v_mfma_f32_16x16x32_bf16 v[0:3], v[180:183], v[212:215], v[0:3]
	s_setprio 0
	s_barrier
	s_add_i32 s52, s52, 2
	s_add_u32 s24, s24, 0x100
	s_addc_u32 s25, s25, 0
	s_add_u32 s50, s50, 0x100
	s_addc_u32 s51, s51, 0
	s_cmp_gt_u32 s52, 13
	s_cbranch_scc0 .LBB0_683
	s_and_b64 vcc, exec, s[12:13]
	s_cbranch_vccz .LBB0_686
	s_barrier

; #define PG8_STAGE(bufoff, gbase, voff) do { _Pragma("unroll") for (int _i = 0; _i < 2; ++_i) \
;         __builtin_amdgcn_global_load_lds((const unsigned*)((const char*)(gbase) + (voff)[_i]), (LAS unsigned*)(lds + (bufoff) + ldsw + _i * 8192), 16, 0, 0); } while (0)
; #define PG8_LDA(dst, b, h) do { _Pragma("unroll") for (int m = 0; m < 4; ++m) _Pragma("unroll") for (int k = 0; k < 2; ++k) dst[m][k] = *(const LAS bf16x8*)(lds + PG8_SA(b, h) + aoff + m * 2048 + k * 1024); } while (0)
; #define PG8_LDB(dst, b, h) do { _Pragma("unroll") for (int n = 0; n < 2; ++n) _Pragma("unroll") for (int k = 0; k < 2; ++k) dst[n][k] = *(const LAS bf16x8*)(lds + PG8_SB(b, h) + boff + n * 2048 + k * 1024); } while (0)
; #define PG8_MMA(ai, bj, At, Bt) do { __builtin_amdgcn_s_setprio(1); _Pragma("unroll") for (int m = 0; m < 4; ++m) _Pragma("unroll") for (int n = 0; n < 2; ++n) _Pragma("unroll") for (int k = 0; k < 2; ++k) \
;         acc[ai][bj][m][n] = __builtin_amdgcn_mfma_f32_16x16x32_bf16(Bt[n][k], At[m][k], acc[ai][bj][m][n], 0, 0, 0); __builtin_amdgcn_s_setprio(0); } while (0)
; #define PG8_WAIT_V(n) asm volatile("s_waitcnt vmcnt(" #n ")" ::: "memory")
; #define PG8_WAIT_L(n) asm volatile("s_waitcnt lgkmcnt(" #n ")" ::: "memory")
; #define PG8_BAR __builtin_amdgcn_s_barrier()
; template <class Epi, class Sched, bool ALIGN_EPI, bool SP2>
; __device__ __forceinline__ void gemm_phase(LAS unsigned char* lds, const Gemm g, const Sched& S, const Epi& E) {
;     ...
;         for (int t = 0; t < nt; t += 2) {
;             const bool last = (t == nt - 2);
;             const char* a1 = cA + (size_t)(t + 1) * kstep;
;             const char* a2 = last ? nA : cA + (size_t)(t + 2) * kstep; const char* b2 = last ? nB : cB + (size_t)(t + 2) * kstep;
;             const char* a3 = a2 + kstep; const char* b3 = b2 + kstep;
;             if constexpr (SP2) {
;             PG8_LDB(B0, 0, 0); PG8_LDB(B1, 0, 1); PG8_SCHED; PG8_LDA(At, 0, 0); PG8_STAGE(PG8_SA(1, 1), a1 + hstep, voffA);
;             PG8_WAIT_V(8); PG8_WAIT_L(0); PG8_BAR; PG8_MMA(0, 0, At, B0); PG8_MMA(0, 1, At, B1); PG8_BAR; PG8_SCHED;
;             PG8_LDA(At, 0, 1); PG8_STAGE(PG8_SB(0, 0), b2, voffB); PG8_STAGE(PG8_SB(0, 1), b2 + hstep, voffB); PG8_STAGE(PG8_SA(0, 0), a2, voffA);
;             PG8_WAIT_V(8); PG8_WAIT_L(0); PG8_BAR; PG8_MMA(1, 0, At, B0); PG8_MMA(1, 1, At, B1); PG8_BAR; PG8_SCHED;
.LBB0_766:
	s_add_i32 m0, s37, 0xc000
	s_nop 0
	global_load_lds_dwordx4 v152, s[24:25]
	s_add_i32 m0, s37, 0xe000
	s_nop 0
	global_load_lds_dwordx4 v154, s[24:25]
	ds_read_b128 v[120:123], v169
	ds_read_b128 v[124:127], v169 offset:1024
	ds_read_b128 v[136:139], v169 offset:2048
	ds_read_b128 v[140:143], v169 offset:3072
	ds_read_b128 v[160:163], v170
	ds_read_b128 v[172:175], v170 offset:1024
	ds_read_b128 v[176:179], v170 offset:2048
	ds_read_b128 v[180:183], v170 offset:3072
	ds_read_b128 v[184:187], v171
	ds_read_b128 v[188:191], v171 offset:1024
	ds_read_b128 v[192:195], v171 offset:2048
	ds_read_b128 v[196:199], v171 offset:3072
	ds_read_b128 v[200:203], v171 offset:4096
	ds_read_b128 v[204:207], v171 offset:5120
	ds_read_b128 v[208:211], v171 offset:6144
	ds_read_b128 v[212:215], v171 offset:7168
	s_add_u32 s26, s24, 0x100
	s_addc_u32 s27, s25, 0
	s_cmp_eq_u32 s56, 40
	s_cselect_b32 s31, s5, s27
	s_cselect_b32 s30, s4, s26
	s_cselect_b32 s29, s23, s55
	s_cselect_b32 s28, s22, s54
	s_waitcnt vmcnt(8)
	s_waitcnt lgkmcnt(0)
	s_barrier
	s_setprio 1
	s_waitcnt lgkmcnt(0)
	v_mfma_f32_16x16x32_bf16 v[132:135], v[120:123], v[184:187], v[132:135]
	v_mfma_f32_16x16x32_bf16 v[128:131], v[136:139], v[184:187], v[128:131]
	v_mfma_f32_16x16x32_bf16 v[108:111], v[120:123], v[192:195], v[108:111]
	v_mfma_f32_16x16x32_bf16 v[104:107], v[136:139], v[192:195], v[104:107]
	v_mfma_f32_16x16x32_bf16 v[92:95], v[120:123], v[200:203], v[92:95]
	v_mfma_f32_16x16x32_bf16 v[88:91], v[136:139], v[200:203], v[88:91]
	v_mfma_f32_16x16x32_bf16 v[76:79], v[120:123], v[208:211], v[76:79]
	v_mfma_f32_16x16x32_bf16 v[72:75], v[136:139], v[208:211], v[72:75]
	v_mfma_f32_16x16x32_bf16 v[132:135], v[124:127], v[188:191], v[132:135]
	v_mfma_f32_16x16x32_bf16 v[128:131], v[140:143], v[188:191], v[128:131]
	v_mfma_f32_16x16x32_bf16 v[108:111], v[124:127], v[196:199], v[108:111]
	v_mfma_f32_16x16x32_bf16 v[104:107], v[140:143], v[196:199], v[104:107]
	v_mfma_f32_16x16x32_bf16 v[92:95], v[124:127], v[204:207], v[92:95]
	v_mfma_f32_16x16x32_bf16 v[88:91], v[140:143], v[204:207], v[88:91]
	v_mfma_f32_16x16x32_bf16 v[76:79], v[124:127], v[212:215], v[76:79]
	v_mfma_f32_16x16x32_bf16 v[72:75], v[140:143], v[212:215], v[72:75]
	s_nop 0
	s_nop 0
	v_mfma_f32_16x16x32_bf16 v[116:119], v[160:163], v[184:187], v[116:119]
	v_mfma_f32_16x16x32_bf16 v[112:115], v[176:179], v[184:187], v[112:115]
	v_mfma_f32_16x16x32_bf16 v[100:103], v[160:163], v[192:195], v[100:103]
	v_mfma_f32_16x16x32_bf16 v[96:99], v[176:179], v[192:195], v[96:99]
	v_mfma_f32_16x16x32_bf16 v[84:87], v[160:163], v[200:203], v[84:87]
	v_mfma_f32_16x16x32_bf16 v[80:83], v[176:179], v[200:203], v[80:83]
	v_mfma_f32_16x16x32_bf16 v[68:71], v[160:163], v[208:211], v[68:71]
	v_mfma_f32_16x16x32_bf16 v[64:67], v[176:179], v[208:211], v[64:67]
	v_mfma_f32_16x16x32_bf16 v[116:119], v[172:175], v[188:191], v[116:119]
	v_mfma_f32_16x16x32_bf16 v[112:115], v[180:183], v[188:191], v[112:115]
	v_mfma_f32_16x16x32_bf16 v[100:103], v[172:175], v[196:199], v[100:103]
	v_mfma_f32_16x16x32_bf16 v[96:99], v[180:183], v[196:199], v[96:99]
	v_mfma_f32_16x16x32_bf16 v[84:87], v[172:175], v[204:207], v[84:87]
	v_mfma_f32_16x16x32_bf16 v[80:83], v[180:183], v[204:207], v[80:83]
	v_mfma_f32_16x16x32_bf16 v[68:71], v[172:175], v[212:215], v[68:71]
	v_mfma_f32_16x16x32_bf16 v[64:67], v[180:183], v[212:215], v[64:67]
	s_setprio 0
	s_barrier
	s_add_i32 s24, s48, s36
	s_mov_b32 m0, s24
	s_nop 0
	global_load_lds_dwordx4 v146, s[28:29]
	s_add_i32 m0, s24, 0x2000
	s_add_u32 s24, s28, 0xb0000
	s_addc_u32 s25, s29, 0
	s_add_i32 s57, s49, s36
	global_load_lds_dwordx4 v150, s[28:29]
	s_mov_b32 m0, s57
	s_nop 0
	global_load_lds_dwordx4 v146, s[24:25]
	s_add_i32 m0, s57, 0x2000
	s_nop 0
	global_load_lds_dwordx4 v150, s[24:25]
	s_mov_b32 m0, s37
	s_nop 0
	global_load_lds_dwordx4 v144, s[30:31]
	s_mov_b32 m0, s38
	s_nop 2
	global_load_lds_dwordx4 v148, s[30:31]
	ds_read_b128 v[184:187], v171 offset:16384
	ds_read_b128 v[188:191], v171 offset:17408
	ds_read_b128 v[192:195], v171 offset:18432
	ds_read_b128 v[196:199], v171 offset:19456
	ds_read_b128 v[200:203], v171 offset:20480
	ds_read_b128 v[204:207], v171 offset:21504
	ds_read_b128 v[208:211], v171 offset:22528
	ds_read_b128 v[212:215], v171 offset:23552
	s_waitcnt vmcnt(8)
	s_waitcnt lgkmcnt(0)
	s_barrier
	s_setprio 1
	s_waitcnt lgkmcnt(0)
	v_mfma_f32_16x16x32_bf16 v[60:63], v[120:123], v[184:187], v[60:63]
	v_mfma_f32_16x16x32_bf16 v[56:59], v[136:139], v[184:187], v[56:59]
	v_mfma_f32_16x16x32_bf16 v[44:47], v[120:123], v[192:195], v[44:47]
	v_mfma_f32_16x16x32_bf16 v[40:43], v[136:139], v[192:195], v[40:43]
	v_mfma_f32_16x16x32_bf16 v[28:31], v[120:123], v[200:203], v[28:31]
	v_mfma_f32_16x16x32_bf16 v[24:27], v[136:139], v[200:203], v[24:27]
	v_mfma_f32_16x16x32_bf16 v[12:15], v[120:123], v[208:211], v[12:15]
	v_mfma_f32_16x16x32_bf16 v[8:11], v[136:139], v[208:211], v[8:11]
	v_mfma_f32_16x16x32_bf16 v[60:63], v[124:127], v[188:191], v[60:63]
	v_mfma_f32_16x16x32_bf16 v[56:59], v[140:143], v[188:191], v[56:59]
	v_mfma_f32_16x16x32_bf16 v[44:47], v[124:127], v[196:199], v[44:47]
	v_mfma_f32_16x16x32_bf16 v[40:43], v[140:143], v[196:199], v[40:43]
	v_mfma_f32_16x16x32_bf16 v[28:31], v[124:127], v[204:207], v[28:31]
	v_mfma_f32_16x16x32_bf16 v[24:27], v[140:143], v[204:207], v[24:27]
	v_mfma_f32_16x16x32_bf16 v[12:15], v[124:127], v[212:215], v[12:15]
	v_mfma_f32_16x16x32_bf16 v[8:11], v[140:143], v[212:215], v[8:11]
	s_nop 0
	s_nop 0
	v_mfma_f32_16x16x32_bf16 v[52:55], v[160:163], v[184:187], v[52:55]
	v_mfma_f32_16x16x32_bf16 v[48:51], v[176:179], v[184:187], v[48:51]
	v_mfma_f32_16x16x32_bf16 v[36:39], v[160:163], v[192:195], v[36:39]
	v_mfma_f32_16x16x32_bf16 v[32:35], v[176:179], v[192:195], v[32:35]
	v_mfma_f32_16x16x32_bf16 v[20:23], v[160:163], v[200:203], v[20:23]
	v_mfma_f32_16x16x32_bf16 v[16:19], v[176:179], v[200:203], v[16:19]
	v_mfma_f32_16x16x32_bf16 v[4:7], v[160:163], v[208:211], v[4:7]
	v_mfma_f32_16x16x32_bf16 v[0:3], v[176:179], v[208:211], v[0:3]
	v_mfma_f32_16x16x32_bf16 v[52:55], v[172:175], v[188:191], v[52:55]
	v_mfma_f32_16x16x32_bf16 v[48:51], v[180:183], v[188:191], v[48:51]
	v_mfma_f32_16x16x32_bf16 v[36:39], v[172:175], v[196:199], v[36:39]
	v_mfma_f32_16x16x32_bf16 v[32:35], v[180:183], v[196:199], v[32:35]
	v_mfma_f32_16x16x32_bf16 v[20:23], v[172:175], v[204:207], v[20:23]
	v_mfma_f32_16x16x32_bf16 v[16:19], v[180:183], v[204:207], v[16:19]
	v_mfma_f32_16x16x32_bf16 v[4:7], v[172:175], v[212:215], v[4:7]
	v_mfma_f32_16x16x32_bf16 v[0:3], v[180:183], v[212:215], v[0:3]
	s_setprio 0
	s_barrier
; #define PG8_STAGE(bufoff, gbase, voff) do { _Pragma("unroll") for (int _i = 0; _i < 2; ++_i) \
;         __builtin_amdgcn_global_load_lds((const unsigned*)((const char*)(gbase) + (voff)[_i]), (LAS unsigned*)(lds + (bufoff) + ldsw + _i * 8192), 16, 0, 0); } while (0)
; #define PG8_LDA(dst, b, h) do { _Pragma("unroll") for (int m = 0; m < 4; ++m) _Pragma("unroll") for (int k = 0; k < 2; ++k) dst[m][k] = *(const LAS bf16x8*)(lds + PG8_SA(b, h) + aoff + m * 2048 + k * 1024); } while (0)
; #define PG8_LDB(dst, b, h) do { _Pragma("unroll") for (int n = 0; n < 2; ++n) _Pragma("unroll") for (int k = 0; k < 2; ++k) dst[n][k] = *(const LAS bf16x8*)(lds + PG8_SB(b, h) + boff + n * 2048 + k * 1024); } while (0)
; #define PG8_MMA(ai, bj, At, Bt) do { __builtin_amdgcn_s_setprio(1); _Pragma("unroll") for (int m = 0; m < 4; ++m) _Pragma("unroll") for (int n = 0; n < 2; ++n) _Pragma("unroll") for (int k = 0; k < 2; ++k) \
;         acc[ai][bj][m][n] = __builtin_amdgcn_mfma_f32_16x16x32_bf16(Bt[n][k], At[m][k], acc[ai][bj][m][n], 0, 0, 0); __builtin_amdgcn_s_setprio(0); } while (0)
; #define PG8_WAIT_V(n) asm volatile("s_waitcnt vmcnt(" #n ")" ::: "memory")
; #define PG8_WAIT_L(n) asm volatile("s_waitcnt lgkmcnt(" #n ")" ::: "memory")
; #define PG8_BAR __builtin_amdgcn_s_barrier()
; #define PG8_SCHED __builtin_amdgcn_sched_barrier(0)
; template <class Epi, class Sched, bool ALIGN_EPI, bool SP2>
; __device__ __forceinline__ void gemm_phase(LAS unsigned char* lds, const Gemm g, const Sched& S, const Epi& E) {
;     ...
;             PG8_LDB(B0, 1, 0); PG8_LDB(B1, 1, 1); PG8_SCHED; PG8_LDA(At, 1, 0); PG8_STAGE(PG8_SA(0, 1), a2 + hstep, voffA);
;             PG8_WAIT_V(8); PG8_WAIT_L(0); PG8_BAR; PG8_MMA(0, 0, At, B0); PG8_MMA(0, 1, At, B1); PG8_BAR; PG8_SCHED;
;             PG8_LDA(At, 1, 1); PG8_STAGE(PG8_SB(1, 0), b3, voffB); PG8_STAGE(PG8_SB(1, 1), b3 + hstep, voffB); PG8_STAGE(PG8_SA(1, 0), a3, voffA);
;             PG8_WAIT_V(8); PG8_WAIT_L(0); PG8_BAR; PG8_MMA(1, 0, At, B0); PG8_MMA(1, 1, At, B1); PG8_BAR; PG8_SCHED;
	s_add_i32 s57, 0, 0x18000
	s_add_i32 s58, 0, 0x1c000
	v_add_u32_e32 v140, s57, v167
	v_add_u32_e32 v180, s58, v167
	s_add_u32 s24, s30, 0xb0000
	s_addc_u32 s25, s31, 0
	s_mov_b32 m0, s39
	s_nop 0
	global_load_lds_dwordx4 v144, s[24:25]
	s_mov_b32 m0, s40
	s_nop 0
	global_load_lds_dwordx4 v148, s[24:25]
	ds_read_b128 v[120:123], v140
	ds_read_b128 v[124:127], v140 offset:1024
	ds_read_b128 v[136:139], v140 offset:2048
	ds_read_b128 v[140:143], v140 offset:3072
	ds_read_b128 v[160:163], v180
	ds_read_b128 v[172:175], v180 offset:1024
	ds_read_b128 v[176:179], v180 offset:2048
	ds_read_b128 v[180:183], v180 offset:3072
	ds_read_b128 v[184:187], v171 offset:32768
	ds_read_b128 v[188:191], v171 offset:33792
	ds_read_b128 v[192:195], v171 offset:34816
	ds_read_b128 v[196:199], v171 offset:35840
	ds_read_b128 v[200:203], v171 offset:36864
	ds_read_b128 v[204:207], v171 offset:37888
	ds_read_b128 v[208:211], v171 offset:38912
	ds_read_b128 v[212:215], v171 offset:39936
	s_waitcnt vmcnt(8)
	s_waitcnt lgkmcnt(0)
	s_barrier
	s_setprio 1
	s_waitcnt lgkmcnt(0)
	v_mfma_f32_16x16x32_bf16 v[132:135], v[120:123], v[184:187], v[132:135]
	v_mfma_f32_16x16x32_bf16 v[128:131], v[136:139], v[184:187], v[128:131]
	v_mfma_f32_16x16x32_bf16 v[108:111], v[120:123], v[192:195], v[108:111]
	v_mfma_f32_16x16x32_bf16 v[104:107], v[136:139], v[192:195], v[104:107]
	v_mfma_f32_16x16x32_bf16 v[92:95], v[120:123], v[200:203], v[92:95]
	v_mfma_f32_16x16x32_bf16 v[88:91], v[136:139], v[200:203], v[88:91]
	v_mfma_f32_16x16x32_bf16 v[76:79], v[120:123], v[208:211], v[76:79]
	v_mfma_f32_16x16x32_bf16 v[72:75], v[136:139], v[208:211], v[72:75]
	v_mfma_f32_16x16x32_bf16 v[132:135], v[124:127], v[188:191], v[132:135]
	v_mfma_f32_16x16x32_bf16 v[128:131], v[140:143], v[188:191], v[128:131]
	v_mfma_f32_16x16x32_bf16 v[108:111], v[124:127], v[196:199], v[108:111]
	v_mfma_f32_16x16x32_bf16 v[104:107], v[140:143], v[196:199], v[104:107]
	v_mfma_f32_16x16x32_bf16 v[92:95], v[124:127], v[204:207], v[92:95]
	v_mfma_f32_16x16x32_bf16 v[88:91], v[140:143], v[204:207], v[88:91]
	v_mfma_f32_16x16x32_bf16 v[76:79], v[124:127], v[212:215], v[76:79]
	v_mfma_f32_16x16x32_bf16 v[72:75], v[140:143], v[212:215], v[72:75]
	s_nop 0
	s_nop 0
	v_mfma_f32_16x16x32_bf16 v[116:119], v[160:163], v[184:187], v[116:119]
	v_mfma_f32_16x16x32_bf16 v[112:115], v[176:179], v[184:187], v[112:115]
	v_mfma_f32_16x16x32_bf16 v[100:103], v[160:163], v[192:195], v[100:103]
	v_mfma_f32_16x16x32_bf16 v[96:99], v[176:179], v[192:195], v[96:99]
	v_mfma_f32_16x16x32_bf16 v[84:87], v[160:163], v[200:203], v[84:87]
	v_mfma_f32_16x16x32_bf16 v[80:83], v[176:179], v[200:203], v[80:83]
	v_mfma_f32_16x16x32_bf16 v[68:71], v[160:163], v[208:211], v[68:71]
	v_mfma_f32_16x16x32_bf16 v[64:67], v[176:179], v[208:211], v[64:67]
	v_mfma_f32_16x16x32_bf16 v[116:119], v[172:175], v[188:191], v[116:119]
	v_mfma_f32_16x16x32_bf16 v[112:115], v[180:183], v[188:191], v[112:115]
	v_mfma_f32_16x16x32_bf16 v[100:103], v[172:175], v[196:199], v[100:103]
	v_mfma_f32_16x16x32_bf16 v[96:99], v[180:183], v[196:199], v[96:99]
	v_mfma_f32_16x16x32_bf16 v[84:87], v[172:175], v[204:207], v[84:87]
	v_mfma_f32_16x16x32_bf16 v[80:83], v[180:183], v[204:207], v[80:83]
	v_mfma_f32_16x16x32_bf16 v[68:71], v[172:175], v[212:215], v[68:71]
	v_mfma_f32_16x16x32_bf16 v[64:67], v[180:183], v[212:215], v[64:67]
	s_setprio 0
	s_barrier
	s_add_u32 s100, s24, 0xfff50080
	s_addc_u32 s101, s25, -1
	s_add_u32 s98, s28, 0x80
	s_addc_u32 s99, s29, 0
	s_add_i32 s24, s57, s36
	s_mov_b32 m0, s24
	s_nop 0
	global_load_lds_dwordx4 v146, s[98:99]
	s_add_i32 m0, s24, 0x2000
	s_add_u32 s24, s28, 0xb0080
	s_addc_u32 s25, s29, 0
	s_add_i32 s28, s58, s36
	global_load_lds_dwordx4 v150, s[98:99]
	s_mov_b32 m0, s28
	s_nop 0
	global_load_lds_dwordx4 v146, s[24:25]
	s_add_i32 m0, s28, 0x2000
	s_nop 0
	global_load_lds_dwordx4 v150, s[24:25]
	s_mov_b32 m0, s45
	s_nop 0
	global_load_lds_dwordx4 v144, s[100:101]
	s_mov_b32 m0, s46
	s_nop 0
	global_load_lds_dwordx4 v148, s[100:101]
	ds_read_b128 v[184:187], v171 offset:49152
	ds_read_b128 v[188:191], v171 offset:50176
	ds_read_b128 v[192:195], v171 offset:51200
	ds_read_b128 v[196:199], v171 offset:52224
	ds_read_b128 v[200:203], v171 offset:53248
	ds_read_b128 v[204:207], v171 offset:54272
	ds_read_b128 v[208:211], v171 offset:55296
	ds_read_b128 v[212:215], v171 offset:56320
	s_waitcnt vmcnt(8)
	s_waitcnt lgkmcnt(0)
	s_barrier
	s_setprio 1
	s_waitcnt lgkmcnt(0)
	v_mfma_f32_16x16x32_bf16 v[60:63], v[120:123], v[184:187], v[60:63]
	v_mfma_f32_16x16x32_bf16 v[56:59], v[136:139], v[184:187], v[56:59]
	v_mfma_f32_16x16x32_bf16 v[44:47], v[120:123], v[192:195], v[44:47]
	v_mfma_f32_16x16x32_bf16 v[40:43], v[136:139], v[192:195], v[40:43]
	v_mfma_f32_16x16x32_bf16 v[28:31], v[120:123], v[200:203], v[28:31]
	v_mfma_f32_16x16x32_bf16 v[24:27], v[136:139], v[200:203], v[24:27]
	v_mfma_f32_16x16x32_bf16 v[12:15], v[120:123], v[208:211], v[12:15]
	v_mfma_f32_16x16x32_bf16 v[8:11], v[136:139], v[208:211], v[8:11]
	v_mfma_f32_16x16x32_bf16 v[60:63], v[124:127], v[188:191], v[60:63]
	v_mfma_f32_16x16x32_bf16 v[56:59], v[140:143], v[188:191], v[56:59]
	v_mfma_f32_16x16x32_bf16 v[44:47], v[124:127], v[196:199], v[44:47]
	v_mfma_f32_16x16x32_bf16 v[40:43], v[140:143], v[196:199], v[40:43]
	v_mfma_f32_16x16x32_bf16 v[28:31], v[124:127], v[204:207], v[28:31]
	v_mfma_f32_16x16x32_bf16 v[24:27], v[140:143], v[204:207], v[24:27]
	v_mfma_f32_16x16x32_bf16 v[12:15], v[124:127], v[212:215], v[12:15]
	v_mfma_f32_16x16x32_bf16 v[8:11], v[140:143], v[212:215], v[8:11]
	s_nop 0
	s_nop 0
	v_mfma_f32_16x16x32_bf16 v[52:55], v[160:163], v[184:187], v[52:55]
	v_mfma_f32_16x16x32_bf16 v[48:51], v[176:179], v[184:187], v[48:51]
	v_mfma_f32_16x16x32_bf16 v[36:39], v[160:163], v[192:195], v[36:39]
	v_mfma_f32_16x16x32_bf16 v[32:35], v[176:179], v[192:195], v[32:35]
	v_mfma_f32_16x16x32_bf16 v[20:23], v[160:163], v[200:203], v[20:23]
	v_mfma_f32_16x16x32_bf16 v[16:19], v[176:179], v[200:203], v[16:19]
	v_mfma_f32_16x16x32_bf16 v[4:7], v[160:163], v[208:211], v[4:7]
	v_mfma_f32_16x16x32_bf16 v[0:3], v[176:179], v[208:211], v[0:3]
	v_mfma_f32_16x16x32_bf16 v[52:55], v[172:175], v[188:191], v[52:55]
	v_mfma_f32_16x16x32_bf16 v[48:51], v[180:183], v[188:191], v[48:51]
	v_mfma_f32_16x16x32_bf16 v[36:39], v[172:175], v[196:199], v[36:39]
	v_mfma_f32_16x16x32_bf16 v[32:35], v[180:183], v[196:199], v[32:35]
	v_mfma_f32_16x16x32_bf16 v[20:23], v[172:175], v[204:207], v[20:23]
	v_mfma_f32_16x16x32_bf16 v[16:19], v[180:183], v[204:207], v[16:19]
	v_mfma_f32_16x16x32_bf16 v[4:7], v[172:175], v[212:215], v[4:7]
	v_mfma_f32_16x16x32_bf16 v[0:3], v[180:183], v[212:215], v[0:3]
	s_setprio 0
	s_barrier
	s_add_i32 s56, s56, 2
	s_add_u32 s54, s54, 0x100
	s_addc_u32 s55, s55, 0
	s_cmp_gt_u32 s56, 41
	s_mov_b64 s[24:25], s[26:27]
	s_cbranch_scc0 .LBB0_766
	s_and_b64 vcc, exec, s[12:13]
	s_cbranch_vccz .LBB0_769
	s_barrier
